# v21 plus 2-wait-state pads between v_cmp and the v_cndmask that reads its mask in the lazy running-max code (hazard hygiene only)
# baseline (speedup 1.0000x reference)
; DI float fexp2(float x) { return __builtin_amdgcn_exp2f(x); }
; DI f32x16 mfma32(bf16x8 a, bf16x8 b, f32x16 c) { return __builtin_amdgcn_mfma_f32_32x32x16_bf16(a, b, c, 0, 0, 0); }
; template <int MASK, bool NEAR, int PASS>
; DI void flash_tile(Flash& st, const bf16x8 (&qf)[4], const char* kbuf, const char* vbuf, int pos0, int qpos, bool on,
;                    const float* lut, float bfar, float* imp_row, float rinv) {
;     ...
; #pragma unroll
;     for (int ks = 0; ks < 4; ++ks) {
;         const int ka = r * 128 + (((2 * ks + h) ^ ((r >> 1) & 7)) << 4);
;         const bf16x8 a0 = *(const bf16x8*)(kbuf + ka);
;         const bf16x8 a1 = *(const bf16x8*)(kbuf + 4096 + ka);
;         s[0] = mfma32(a0, qf[ks], s[0]);
;         s[1] = mfma32(a1, qf[ks], s[1]);
;     }
;     constexpr float c1 = 0.125f * LOG2E;
;     float alpha = 1.f;
;     float rs = 0.f;
;     if (!NEAR) {
;         const float bc = MASK == 2 ? 0.f : bfar;
;         float mref;
;         if (PASS != 2) {
;             float mr = s[0][0];
; #pragma unroll
;             for (int i = 1; i < 16; ++i) mr = fmaxf(mr, s[0][i]);
; #pragma unroll
;             for (int i = 0; i < 16; ++i) mr = fmaxf(mr, s[1][i]);
;             float mx = on ? mr * c1 + bc : -1e30f;
;             mx = fmaxf(mx, __shfl_xor(mx, 32));
;             const float mnew = fmaxf(st.m, mx);
;             alpha = fexp2(st.m - mnew);
;             st.m = mnew;
;             mref = mnew;
;         } else mref = st.m;
;         float bm = on ? bc - mref : -1e30f;
;         if (PASS == 2) bm = on ? bm + __log2f(rinv) : -1e30f;
; #pragma unroll
;         for (int tt = 0; tt < 2; ++tt)
; #pragma unroll
;             for (int i = 0; i < 16; ++i) { const float pv = fexp2(s[tt][i] * c1 + bm); s[tt][i] = pv; rs += pv; }
;     DI bool operator()(int pos0) const {
;         if (kind == 0) return qvalid;
;         if (kind == 1) { const int blk = pos0 >> 8; return qvalid && (blk == cur || ((lo >> blk) & 1ull)); }
;         const int j = pos0 >> 6;
;         if (j >= 128) return qvalid;
;         const unsigned long long x = j < 64 ? lo : hi;
;         return qvalid && ((x >> (j & 63)) & 1ull) != 0ull;
;     }
.LBB0_1094:
	s_waitcnt lgkmcnt(0)
	v_ashrrev_i32_e32 v38, 6, v52
	v_cmp_gt_i32_e32 vcc, 64, v38
	s_nop 1
	v_cndmask_b32_e32 v37, v154, v178, vcc
	v_cndmask_b32_e32 v36, v177, v179, vcc
	v_lshrrev_b64 v[36:37], v38, v[36:37]
	v_and_b32_e32 v36, 1, v36
	v_cmp_eq_u32_e32 vcc, 1, v36
	s_and_b64 s[2:3], s[8:9], vcc
	v_cndmask_b32_e64 v36, 0, 1, s[2:3]
	v_cndmask_b32_e64 v37, 0, 1, s[8:9]
	v_cmp_lt_i32_e32 vcc, s86, v38
	s_nop 1
	v_cndmask_b32_e32 v36, v36, v37, vcc
	v_and_b32_e32 v36, 1, v36
	v_cmp_eq_u32_e64 s[16:17], 1, v36
	v_cmp_ne_u32_e32 vcc, 0, v36
	s_cbranch_vccz .LBB0_1084
	v_add_u32_e32 v40, s24, v190
	ds_read_b128 v[36:39], v40
	ds_read_b128 v[138:141], v40 offset:4096
	v_add_u32_e32 v40, s24, v191
	ds_read_b128 v[150:153], v40
	ds_read_b128 v[134:137], v40 offset:4096
	v_add_u32_e32 v40, s24, v192
	ds_read_b128 v[146:149], v40
	ds_read_b128 v[130:133], v40 offset:4096
	v_add_u32_e32 v40, s24, v193
	ds_read_b128 v[142:145], v40
	ds_read_b128 v[126:129], v40 offset:4096
	v_cmp_le_i32_e32 vcc, v52, v169
	v_add3_u32 v181, s24, v199, v200
	s_and_saveexec_b64 s[2:3], vcc
	s_xor_b64 s[2:3], exec, s[2:3]
	s_cbranch_execz .LBB0_1097
	s_waitcnt lgkmcnt(7)
	v_mfma_f32_32x32x16_bf16 v[52:67], v[36:39], v[94:97], 0
	s_waitcnt lgkmcnt(5)
	v_mfma_f32_32x32x16_bf16 v[52:67], v[150:153], v[98:101], v[52:67]
	v_mfma_f32_32x32x16_bf16 v[36:51], v[138:141], v[94:97], 0
	s_waitcnt lgkmcnt(3)
	v_mfma_f32_32x32x16_bf16 v[52:67], v[146:149], v[102:105], v[52:67]
	v_mfma_f32_32x32x16_bf16 v[36:51], v[134:137], v[98:101], v[36:51]
	s_waitcnt lgkmcnt(1)
	v_mfma_f32_32x32x16_bf16 v[52:67], v[142:145], v[106:109], v[52:67]
	v_mfma_f32_32x32x16_bf16 v[36:51], v[130:133], v[102:105], v[36:51]
	s_nop 10
	v_max_f32_e32 v134, v53, v53
	v_max_f32_e32 v135, v52, v52
	v_max_f32_e32 v134, v135, v134
	v_max3_f32 v130, v134, v54, v55
	v_max3_f32 v130, v130, v56, v57
	v_max3_f32 v130, v130, v58, v59
	v_max3_f32 v130, v130, v60, v61
	s_waitcnt lgkmcnt(0)
	v_mfma_f32_32x32x16_bf16 v[36:51], v[126:129], v[106:109], v[36:51]
	v_max3_f32 v130, v130, v62, v63
	v_max3_f32 v130, v130, v64, v65
	v_max3_f32 v130, v130, v66, v67
	s_nop 8
	v_max3_f32 v126, v130, v36, v37
	v_max3_f32 v126, v126, v38, v39
	v_max3_f32 v126, v126, v40, v41
	v_max3_f32 v126, v126, v42, v43
	v_max3_f32 v126, v126, v44, v45
	v_max3_f32 v126, v126, v46, v47
	v_max3_f32 v126, v126, v48, v49
	v_max3_f32 v126, v126, v50, v51
	v_fmamk_f32 v126, v126, 0x3e38aa3b, v224
	v_cndmask_b32_e64 v126, v215, v126, s[16:17]
	v_mov_b32_e32 v127, v126
	s_nop 1
	v_permlane32_swap_b32_e32 v126, v127
	v_max3_f32 v126, v182, v126, v127
	s_mov_b32 s99, 0x41000000
	v_sub_f32_e32 v127, v126, v182
	v_cmp_lt_f32_e64 s[100:101], s99, v127
	s_nop 1
	v_cndmask_b32_e64 v126, v182, v126, s[100:101]
	v_sub_f32_e32 v128, v224, v126
	v_cndmask_b32_e64 v128, v215, v128, s[16:17]
	v_fmamk_f32 v52, v52, 0x3e38aa3b, v128
	v_exp_f32_e32 v129, v52
	v_fmamk_f32 v52, v53, 0x3e38aa3b, v128
	v_exp_f32_e32 v53, v52
	v_fmamk_f32 v52, v54, 0x3e38aa3b, v128
	v_exp_f32_e32 v54, v52
	v_fmamk_f32 v52, v55, 0x3e38aa3b, v128
	v_exp_f32_e32 v55, v52
	v_fmamk_f32 v52, v56, 0x3e38aa3b, v128
	v_exp_f32_e32 v56, v52
	v_fmamk_f32 v52, v57, 0x3e38aa3b, v128
	v_exp_f32_e32 v57, v52
	v_fmamk_f32 v52, v58, 0x3e38aa3b, v128
	v_exp_f32_e32 v58, v52
	v_fmamk_f32 v52, v59, 0x3e38aa3b, v128
	v_exp_f32_e32 v59, v52
	v_fmamk_f32 v52, v60, 0x3e38aa3b, v128
	v_exp_f32_e32 v60, v52
	v_fmamk_f32 v52, v61, 0x3e38aa3b, v128
	v_exp_f32_e32 v61, v52
	v_fmamk_f32 v52, v62, 0x3e38aa3b, v128
	v_exp_f32_e32 v62, v52
	v_fmamk_f32 v52, v63, 0x3e38aa3b, v128
	v_exp_f32_e32 v63, v52
	v_fmamk_f32 v52, v64, 0x3e38aa3b, v128
	v_exp_f32_e32 v64, v52
	v_fmamk_f32 v52, v65, 0x3e38aa3b, v128
	v_exp_f32_e32 v65, v52
	v_fmamk_f32 v52, v66, 0x3e38aa3b, v128
	v_fmamk_f32 v66, v67, 0x3e38aa3b, v128
	v_exp_f32_e32 v67, v52
	v_add_f32_e32 v52, 0, v129
	v_add_f32_e32 v52, v53, v52
	v_add_f32_e32 v52, v54, v52
	v_add_f32_e32 v52, v55, v52
	v_add_f32_e32 v52, v56, v52
	v_add_f32_e32 v52, v57, v52
	v_add_f32_e32 v52, v58, v52
	v_add_f32_e32 v52, v59, v52
	v_add_f32_e32 v52, v60, v52
	v_add_f32_e32 v52, v61, v52
	v_add_f32_e32 v52, v62, v52
	v_add_f32_e32 v52, v63, v52
	v_exp_f32_e32 v66, v66
	v_fmamk_f32 v36, v36, 0x3e38aa3b, v128
	v_add_f32_e32 v52, v64, v52
	v_exp_f32_e32 v130, v36
	v_fmamk_f32 v36, v37, 0x3e38aa3b, v128
	v_add_f32_e32 v52, v65, v52
	v_exp_f32_e32 v131, v36
	v_fmamk_f32 v36, v38, 0x3e38aa3b, v128
	v_add_f32_e32 v52, v67, v52
	v_exp_f32_e32 v132, v36
	v_fmamk_f32 v36, v39, 0x3e38aa3b, v128
	v_add_f32_e32 v52, v66, v52
	v_exp_f32_e32 v133, v36
	v_fmamk_f32 v37, v40, 0x3e38aa3b, v128
	v_add_f32_e32 v36, v130, v52
	v_exp_f32_e32 v134, v37
	v_fmamk_f32 v37, v41, 0x3e38aa3b, v128
	v_add_f32_e32 v36, v131, v36
	v_exp_f32_e32 v135, v37
	v_fmamk_f32 v37, v42, 0x3e38aa3b, v128
	v_add_f32_e32 v36, v132, v36
	v_exp_f32_e32 v136, v37
	v_fmamk_f32 v37, v43, 0x3e38aa3b, v128
	v_add_f32_e32 v36, v133, v36
	v_exp_f32_e32 v137, v37
	v_fmamk_f32 v37, v44, 0x3e38aa3b, v128
	v_add_f32_e32 v36, v134, v36
	v_exp_f32_e32 v138, v37
	v_fmamk_f32 v37, v45, 0x3e38aa3b, v128
	v_add_f32_e32 v36, v135, v36
	v_exp_f32_e32 v139, v37
	v_fmamk_f32 v37, v46, 0x3e38aa3b, v128
	v_add_f32_e32 v36, v136, v36
	v_exp_f32_e32 v140, v37
	v_add_f32_e32 v36, v137, v36
	v_add_f32_e32 v36, v138, v36
	v_sub_f32_e32 v127, v182, v126
	v_add_f32_e32 v36, v139, v36
	v_exp_f32_e32 v52, v127
	v_add_f32_e32 v127, v140, v36
	v_fmamk_f32 v36, v47, 0x3e38aa3b, v128
	v_exp_f32_e32 v141, v36
	ds_read_b64_tr_b16 v[36:37], v181 offset:8192
	ds_read_b64_tr_b16 v[38:39], v181 offset:9216
	ds_read_b64_tr_b16 v[46:47], v181 offset:9280
	ds_read_b64_tr_b16 v[44:45], v181 offset:8256
	v_cvt_pk_bf16_f32 v43, v58, v59
	v_cvt_pk_bf16_f32 v42, v56, v57
	v_cvt_pk_bf16_f32 v41, v54, v55
	v_cvt_pk_bf16_f32 v40, v129, v53
	s_cmp_eq_u64 s[100:101], 0
	s_cbranch_scc1 .Llz_gatA
	v_pk_mul_f32 v[34:35], v[34:35], v[52:53] op_sel_hi:[1,0]
	v_pk_mul_f32 v[32:33], v[32:33], v[52:53] op_sel_hi:[1,0]
	v_pk_mul_f32 v[30:31], v[30:31], v[52:53] op_sel_hi:[1,0]
	v_pk_mul_f32 v[28:29], v[28:29], v[52:53] op_sel_hi:[1,0]
	v_pk_mul_f32 v[26:27], v[26:27], v[52:53] op_sel_hi:[1,0]
	v_pk_mul_f32 v[24:25], v[24:25], v[52:53] op_sel_hi:[1,0]
	v_pk_mul_f32 v[22:23], v[22:23], v[52:53] op_sel_hi:[1,0]
	v_pk_mul_f32 v[20:21], v[20:21], v[52:53] op_sel_hi:[1,0]
	v_pk_mul_f32 v[18:19], v[18:19], v[52:53] op_sel_hi:[1,0]
	v_pk_mul_f32 v[16:17], v[16:17], v[52:53] op_sel_hi:[1,0]
	v_pk_mul_f32 v[14:15], v[14:15], v[52:53] op_sel_hi:[1,0]
	v_pk_mul_f32 v[12:13], v[12:13], v[52:53] op_sel_hi:[1,0]
	v_pk_mul_f32 v[10:11], v[10:11], v[52:53] op_sel_hi:[1,0]
	v_pk_mul_f32 v[8:9], v[8:9], v[52:53] op_sel_hi:[1,0]
	v_pk_mul_f32 v[6:7], v[6:7], v[52:53] op_sel_hi:[1,0]
	v_pk_mul_f32 v[4:5], v[4:5], v[52:53] op_sel_hi:[1,0]
	s_nop 1

; DI float fexp2(float x) { return __builtin_amdgcn_exp2f(x); }
; DI f32x16 mfma32(bf16x8 a, bf16x8 b, f32x16 c) { return __builtin_amdgcn_mfma_f32_32x32x16_bf16(a, b, c, 0, 0, 0); }
; template <int MASK, bool NEAR, int PASS>
; DI void flash_tile(Flash& st, const bf16x8 (&qf)[4], const char* kbuf, const char* vbuf, int pos0, int qpos, bool on,
;                    const float* lut, float bfar, float* imp_row, float rinv) {
;     ...
; #pragma unroll
;     for (int ks = 0; ks < 4; ++ks) {
;         const int ka = r * 128 + (((2 * ks + h) ^ ((r >> 1) & 7)) << 4);
;         const bf16x8 a0 = *(const bf16x8*)(kbuf + ka);
;         const bf16x8 a1 = *(const bf16x8*)(kbuf + 4096 + ka);
;         s[0] = mfma32(a0, qf[ks], s[0]);
;         s[1] = mfma32(a1, qf[ks], s[1]);
;     }
;     constexpr float c1 = 0.125f * LOG2E;
;     float alpha = 1.f;
;     float rs = 0.f;
;     if (!NEAR) {
;         const float bc = MASK == 2 ? 0.f : bfar;
;         float mref;
;         if (PASS != 2) {
;             float mr = s[0][0];
; #pragma unroll
;             for (int i = 1; i < 16; ++i) mr = fmaxf(mr, s[0][i]);
; #pragma unroll
;             for (int i = 0; i < 16; ++i) mr = fmaxf(mr, s[1][i]);
;             float mx = on ? mr * c1 + bc : -1e30f;
;             mx = fmaxf(mx, __shfl_xor(mx, 32));
;             const float mnew = fmaxf(st.m, mx);
;             alpha = fexp2(st.m - mnew);
;             st.m = mnew;
;             mref = mnew;
;         } else mref = st.m;
;         float bm = on ? bc - mref : -1e30f;
;         if (PASS == 2) bm = on ? bm + __log2f(rinv) : -1e30f;
; #pragma unroll
;         for (int tt = 0; tt < 2; ++tt)
; #pragma unroll
;             for (int i = 0; i < 16; ++i) { const float pv = fexp2(s[tt][i] * c1 + bm); s[tt][i] = pv; rs += pv; }
.LBB0_1133:
	s_andn2_saveexec_b64 s[0:1], s[0:1]
	s_cbranch_execz .LBB0_1126
	s_waitcnt lgkmcnt(7)
	v_mfma_f32_32x32x16_bf16 v[52:67], v[36:39], v[94:97], 0
	s_waitcnt lgkmcnt(5)
	v_mfma_f32_32x32x16_bf16 v[52:67], v[150:153], v[98:101], v[52:67]
	v_mfma_f32_32x32x16_bf16 v[36:51], v[138:141], v[94:97], 0
	s_waitcnt lgkmcnt(3)
	v_mfma_f32_32x32x16_bf16 v[52:67], v[146:149], v[102:105], v[52:67]
	v_mfma_f32_32x32x16_bf16 v[36:51], v[134:137], v[98:101], v[36:51]
	s_waitcnt lgkmcnt(1)
	v_mfma_f32_32x32x16_bf16 v[52:67], v[142:145], v[106:109], v[52:67]
	v_mfma_f32_32x32x16_bf16 v[36:51], v[130:133], v[102:105], v[36:51]
	s_nop 10
	v_max_f32_e32 v134, v53, v53
	v_max_f32_e32 v135, v52, v52
	v_max_f32_e32 v134, v135, v134
	v_max3_f32 v130, v134, v54, v55
	v_max3_f32 v130, v130, v56, v57
	v_max3_f32 v130, v130, v58, v59
	v_max3_f32 v130, v130, v60, v61
	s_waitcnt lgkmcnt(0)
	v_mfma_f32_32x32x16_bf16 v[36:51], v[126:129], v[106:109], v[36:51]
	v_max3_f32 v130, v130, v62, v63
	v_max3_f32 v130, v130, v64, v65
	v_max3_f32 v130, v130, v66, v67
	s_nop 8
	v_max3_f32 v126, v130, v36, v37
	v_max3_f32 v126, v126, v38, v39
	v_max3_f32 v126, v126, v40, v41
	v_max3_f32 v126, v126, v42, v43
	v_max3_f32 v126, v126, v44, v45
	v_max3_f32 v126, v126, v46, v47
	v_max3_f32 v126, v126, v48, v49
	v_max3_f32 v126, v126, v50, v51
	v_fmamk_f32 v126, v126, 0x3e38aa3b, v224
	v_cndmask_b32_e64 v126, v215, v126, s[8:9]
	v_mov_b32_e32 v127, v126
	s_nop 1
	v_permlane32_swap_b32_e32 v126, v127
	v_max3_f32 v126, v171, v126, v127
	s_mov_b32 s99, 0x41000000
	v_sub_f32_e32 v127, v126, v171
	v_cmp_lt_f32_e64 s[100:101], s99, v127
	s_nop 1
	v_cndmask_b32_e64 v126, v171, v126, s[100:101]
	v_sub_f32_e32 v128, v224, v126
	v_cndmask_b32_e64 v128, v215, v128, s[8:9]
	v_fmamk_f32 v52, v52, 0x3e38aa3b, v128
	v_exp_f32_e32 v129, v52
	v_fmamk_f32 v52, v53, 0x3e38aa3b, v128
	v_exp_f32_e32 v53, v52
	v_fmamk_f32 v52, v54, 0x3e38aa3b, v128
	v_exp_f32_e32 v54, v52
	v_fmamk_f32 v52, v55, 0x3e38aa3b, v128
	v_exp_f32_e32 v55, v52
	v_fmamk_f32 v52, v56, 0x3e38aa3b, v128
	v_exp_f32_e32 v56, v52
	v_fmamk_f32 v52, v57, 0x3e38aa3b, v128
	v_exp_f32_e32 v57, v52
	v_fmamk_f32 v52, v58, 0x3e38aa3b, v128
	v_exp_f32_e32 v58, v52
	v_fmamk_f32 v52, v59, 0x3e38aa3b, v128
	v_exp_f32_e32 v59, v52
	v_fmamk_f32 v52, v60, 0x3e38aa3b, v128
	v_exp_f32_e32 v60, v52
	v_fmamk_f32 v52, v61, 0x3e38aa3b, v128
	v_exp_f32_e32 v61, v52
	v_fmamk_f32 v52, v62, 0x3e38aa3b, v128
	v_exp_f32_e32 v62, v52
	v_fmamk_f32 v52, v63, 0x3e38aa3b, v128
	v_exp_f32_e32 v63, v52
	v_fmamk_f32 v52, v64, 0x3e38aa3b, v128
	v_exp_f32_e32 v64, v52
	v_fmamk_f32 v52, v65, 0x3e38aa3b, v128
	v_exp_f32_e32 v65, v52
	v_fmamk_f32 v52, v66, 0x3e38aa3b, v128
	v_fmamk_f32 v66, v67, 0x3e38aa3b, v128
	v_exp_f32_e32 v67, v52
	v_add_f32_e32 v52, 0, v129
	v_add_f32_e32 v52, v53, v52
	v_add_f32_e32 v52, v54, v52
	v_add_f32_e32 v52, v55, v52
	v_add_f32_e32 v52, v56, v52
	v_add_f32_e32 v52, v57, v52
	v_add_f32_e32 v52, v58, v52
	v_add_f32_e32 v52, v59, v52
	v_add_f32_e32 v52, v60, v52
	v_add_f32_e32 v52, v61, v52
	v_add_f32_e32 v52, v62, v52
	v_add_f32_e32 v52, v63, v52
	v_exp_f32_e32 v66, v66
	v_fmamk_f32 v36, v36, 0x3e38aa3b, v128
	v_add_f32_e32 v52, v64, v52
	v_exp_f32_e32 v130, v36
	v_fmamk_f32 v36, v37, 0x3e38aa3b, v128
	v_add_f32_e32 v52, v65, v52
	v_exp_f32_e32 v131, v36
	v_fmamk_f32 v36, v38, 0x3e38aa3b, v128
	v_add_f32_e32 v52, v67, v52
	v_exp_f32_e32 v132, v36
	v_fmamk_f32 v36, v39, 0x3e38aa3b, v128
	v_add_f32_e32 v52, v66, v52
	v_exp_f32_e32 v133, v36
	v_fmamk_f32 v37, v40, 0x3e38aa3b, v128
	v_add_f32_e32 v36, v130, v52
	v_exp_f32_e32 v134, v37
	v_fmamk_f32 v37, v41, 0x3e38aa3b, v128
	v_add_f32_e32 v36, v131, v36
	v_exp_f32_e32 v135, v37
	v_fmamk_f32 v37, v42, 0x3e38aa3b, v128
	v_add_f32_e32 v36, v132, v36
	v_exp_f32_e32 v136, v37
	v_fmamk_f32 v37, v43, 0x3e38aa3b, v128
	v_add_f32_e32 v36, v133, v36
	v_exp_f32_e32 v137, v37
	v_fmamk_f32 v37, v44, 0x3e38aa3b, v128
	v_add_f32_e32 v36, v134, v36
	v_exp_f32_e32 v138, v37
	v_fmamk_f32 v37, v45, 0x3e38aa3b, v128
	v_add_f32_e32 v36, v135, v36
	v_exp_f32_e32 v139, v37
	v_fmamk_f32 v37, v46, 0x3e38aa3b, v128
	v_add_f32_e32 v36, v136, v36
	v_exp_f32_e32 v140, v37
	v_add_f32_e32 v36, v137, v36
	v_add_f32_e32 v36, v138, v36
	v_sub_f32_e32 v127, v171, v126
	v_add_f32_e32 v36, v139, v36
	v_exp_f32_e32 v52, v127
	v_add_f32_e32 v127, v140, v36
	v_fmamk_f32 v36, v47, 0x3e38aa3b, v128
	v_exp_f32_e32 v141, v36
	ds_read_b64_tr_b16 v[36:37], v2 offset:8192
	ds_read_b64_tr_b16 v[38:39], v2 offset:9216
	ds_read_b64_tr_b16 v[46:47], v2 offset:9280
	ds_read_b64_tr_b16 v[44:45], v2 offset:8256
	v_cvt_pk_bf16_f32 v43, v58, v59
	v_cvt_pk_bf16_f32 v42, v56, v57
	v_cvt_pk_bf16_f32 v41, v54, v55
	v_cvt_pk_bf16_f32 v40, v129, v53
	s_cmp_eq_u64 s[100:101], 0
	s_cbranch_scc1 .Llz_gatB
	v_pk_mul_f32 v[34:35], v[34:35], v[52:53] op_sel_hi:[1,0]
	v_pk_mul_f32 v[32:33], v[32:33], v[52:53] op_sel_hi:[1,0]
	v_pk_mul_f32 v[30:31], v[30:31], v[52:53] op_sel_hi:[1,0]
	v_pk_mul_f32 v[28:29], v[28:29], v[52:53] op_sel_hi:[1,0]
	v_pk_mul_f32 v[26:27], v[26:27], v[52:53] op_sel_hi:[1,0]
	v_pk_mul_f32 v[24:25], v[24:25], v[52:53] op_sel_hi:[1,0]
	v_pk_mul_f32 v[22:23], v[22:23], v[52:53] op_sel_hi:[1,0]
	v_pk_mul_f32 v[20:21], v[20:21], v[52:53] op_sel_hi:[1,0]
	v_pk_mul_f32 v[18:19], v[18:19], v[52:53] op_sel_hi:[1,0]
	v_pk_mul_f32 v[16:17], v[16:17], v[52:53] op_sel_hi:[1,0]
	v_pk_mul_f32 v[14:15], v[14:15], v[52:53] op_sel_hi:[1,0]
	v_pk_mul_f32 v[12:13], v[12:13], v[52:53] op_sel_hi:[1,0]
	v_pk_mul_f32 v[10:11], v[10:11], v[52:53] op_sel_hi:[1,0]
	v_pk_mul_f32 v[8:9], v[8:9], v[52:53] op_sel_hi:[1,0]
	v_pk_mul_f32 v[6:7], v[6:7], v[52:53] op_sel_hi:[1,0]
	v_pk_mul_f32 v[4:5], v[4:5], v[52:53] op_sel_hi:[1,0]
	s_nop 1

; DI float fexp2(float x) { return __builtin_amdgcn_exp2f(x); }
; DI f32x16 mfma32(bf16x8 a, bf16x8 b, f32x16 c) { return __builtin_amdgcn_mfma_f32_32x32x16_bf16(a, b, c, 0, 0, 0); }
; template <int MASK, bool NEAR, int PASS>
; DI void flash_tile(Flash& st, const bf16x8 (&qf)[4], const char* kbuf, const char* vbuf, int pos0, int qpos, bool on,
;                    const float* lut, float bfar, float* imp_row, float rinv) {
;     ...
; #pragma unroll
;     for (int ks = 0; ks < 4; ++ks) {
;         const int ka = r * 128 + (((2 * ks + h) ^ ((r >> 1) & 7)) << 4);
;         const bf16x8 a0 = *(const bf16x8*)(kbuf + ka);
;         const bf16x8 a1 = *(const bf16x8*)(kbuf + 4096 + ka);
;         s[0] = mfma32(a0, qf[ks], s[0]);
;         s[1] = mfma32(a1, qf[ks], s[1]);
;     }
;     constexpr float c1 = 0.125f * LOG2E;
;     float alpha = 1.f;
;     float rs = 0.f;
;     if (!NEAR) {
;         const float bc = MASK == 2 ? 0.f : bfar;
;         float mref;
;         if (PASS != 2) {
;             float mr = s[0][0];
; #pragma unroll
;             for (int i = 1; i < 16; ++i) mr = fmaxf(mr, s[0][i]);
; #pragma unroll
;             for (int i = 0; i < 16; ++i) mr = fmaxf(mr, s[1][i]);
;             float mx = on ? mr * c1 + bc : -1e30f;
;             mx = fmaxf(mx, __shfl_xor(mx, 32));
;             const float mnew = fmaxf(st.m, mx);
;             alpha = fexp2(st.m - mnew);
;             st.m = mnew;
;             mref = mnew;
;         } else mref = st.m;
;         float bm = on ? bc - mref : -1e30f;
;         if (PASS == 2) bm = on ? bm + __log2f(rinv) : -1e30f;
; #pragma unroll
;         for (int tt = 0; tt < 2; ++tt)
; #pragma unroll
;             for (int i = 0; i < 16; ++i) { const float pv = fexp2(s[tt][i] * c1 + bm); s[tt][i] = pv; rs += pv; }
;     DI bool operator()(int pos0) const {
;         if (kind == 0) return qvalid;
;         if (kind == 1) { const int blk = pos0 >> 8; return qvalid && (blk == cur || ((lo >> blk) & 1ull)); }
;         const int j = pos0 >> 6;
;         if (j >= 128) return qvalid;
;         const unsigned long long x = j < 64 ? lo : hi;
;         return qvalid && ((x >> (j & 63)) & 1ull) != 0ull;
;     }
.LBB0_1366:
	s_ashr_i32 s2, s22, 6
	s_cmpk_gt_i32 s2, 0x7f
	s_cselect_b64 vcc, -1, 0
	s_cmp_lt_i32 s2, 64
	s_cselect_b64 s[0:1], -1, 0
	v_cndmask_b32_e64 v5, v1, v157, s[0:1]
	v_cndmask_b32_e64 v4, v154, v174, s[0:1]
	v_lshrrev_b64 v[4:5], s2, v[4:5]
	v_and_b32_e32 v2, 1, v4
	v_cmp_eq_u32_e64 s[0:1], 1, v2
	s_and_b64 s[0:1], s[8:9], s[0:1]
	v_cndmask_b32_e64 v180, 0, 1, s[8:9]
	v_cndmask_b32_e64 v2, 0, 1, s[0:1]
	v_cndmask_b32_e32 v2, v2, v180, vcc
	v_and_b32_e32 v2, 1, v2
	v_cmp_eq_u32_e64 s[0:1], 1, v2
	v_cmp_ne_u32_e32 vcc, 0, v2
	s_cbranch_vccz .LBB0_1372
	ds_read_b128 v[50:53], v190
	ds_read_b128 v[138:141], v190 offset:4096
	ds_read_b128 v[150:153], v191
	ds_read_b128 v[12:15], v191 offset:4096
	ds_read_b128 v[146:149], v192
	ds_read_b128 v[8:11], v192 offset:4096
	ds_read_b128 v[142:145], v193
	ds_read_b128 v[4:7], v193 offset:4096
	s_add_i32 s2, s22, 0xb0
	v_cmp_le_i32_e32 vcc, s2, v226
	s_and_saveexec_b64 s[2:3], vcc
	s_xor_b64 s[2:3], exec, s[2:3]
	s_cbranch_execz .LBB0_1369
	s_waitcnt lgkmcnt(7)
	v_mfma_f32_32x32x16_bf16 v[66:81], v[50:53], v[94:97], 0
	s_waitcnt lgkmcnt(5)
	v_mfma_f32_32x32x16_bf16 v[66:81], v[150:153], v[98:101], v[66:81]
	v_mfma_f32_32x32x16_bf16 v[50:65], v[138:141], v[94:97], 0
	s_waitcnt lgkmcnt(3)
	v_mfma_f32_32x32x16_bf16 v[66:81], v[146:149], v[102:105], v[66:81]
	v_mfma_f32_32x32x16_bf16 v[50:65], v[12:15], v[98:101], v[50:65]
	s_waitcnt lgkmcnt(1)
	v_mfma_f32_32x32x16_bf16 v[66:81], v[142:145], v[106:109], v[66:81]
	v_mfma_f32_32x32x16_bf16 v[50:65], v[8:11], v[102:105], v[50:65]
	s_nop 10
	v_max3_f32 v2, v66, v67, v68
	v_max_f32_e32 v2, v2, v69
	v_max3_f32 v2, v2, v70, v71
	v_max3_f32 v2, v2, v72, v73
	v_max3_f32 v2, v2, v74, v75
	s_waitcnt lgkmcnt(0)
	v_mfma_f32_32x32x16_bf16 v[50:65], v[4:7], v[106:109], v[50:65]
	v_max3_f32 v2, v2, v76, v77
	v_max3_f32 v2, v2, v78, v79
	v_max3_f32 v2, v2, v80, v81
	s_nop 8
	v_max3_f32 v2, v2, v50, v51
	v_max3_f32 v2, v2, v52, v53
	v_max3_f32 v2, v2, v54, v55
	v_max3_f32 v2, v2, v56, v57
	v_max3_f32 v2, v2, v58, v59
	v_max3_f32 v2, v2, v60, v61
	v_max3_f32 v2, v2, v62, v63
	v_max3_f32 v2, v2, v64, v65
	v_fmamk_f32 v2, v2, 0x3e38aa3b, v225
	v_cndmask_b32_e64 v2, v215, v2, s[0:1]
	v_mov_b32_e32 v4, v2
	s_nop 1
	v_permlane32_swap_b32_e32 v2, v4
	v_max3_f32 v138, v181, v2, v4
	v_sub_f32_e32 v4, v138, v181
	v_cmp_lt_f32_e32 vcc, 0x41000000, v4
	s_nop 1
	v_cndmask_b32_e32 v138, v181, v138, vcc
	s_mov_b64 s[100:101], vcc
	v_sub_f32_e32 v4, v225, v138
	v_cndmask_b32_e64 v139, v215, v4, s[0:1]
	v_fmamk_f32 v4, v66, 0x3e38aa3b, v139
	v_exp_f32_e32 v8, v4
	v_fmamk_f32 v4, v67, 0x3e38aa3b, v139
	v_exp_f32_e32 v12, v4
	v_fmamk_f32 v4, v68, 0x3e38aa3b, v139
	v_exp_f32_e32 v9, v4
	v_fmamk_f32 v4, v69, 0x3e38aa3b, v139
	v_exp_f32_e32 v13, v4
	v_fmamk_f32 v4, v70, 0x3e38aa3b, v139
	v_exp_f32_e32 v10, v4
	v_fmamk_f32 v4, v71, 0x3e38aa3b, v139
	v_exp_f32_e32 v14, v4
	v_fmamk_f32 v4, v72, 0x3e38aa3b, v139
	v_exp_f32_e32 v11, v4
	v_fmamk_f32 v4, v73, 0x3e38aa3b, v139
	v_exp_f32_e32 v15, v4
	v_fmamk_f32 v4, v74, 0x3e38aa3b, v139
	v_exp_f32_e32 v66, v4
	v_fmamk_f32 v4, v75, 0x3e38aa3b, v139
	v_exp_f32_e32 v67, v4
	v_fmamk_f32 v4, v76, 0x3e38aa3b, v139
	v_exp_f32_e32 v68, v4
	v_fmamk_f32 v4, v77, 0x3e38aa3b, v139
	v_exp_f32_e32 v69, v4
	v_fmamk_f32 v4, v78, 0x3e38aa3b, v139
	v_exp_f32_e32 v70, v4
	v_fmamk_f32 v4, v79, 0x3e38aa3b, v139
	v_exp_f32_e32 v71, v4
	v_fmamk_f32 v4, v80, 0x3e38aa3b, v139
	v_exp_f32_e32 v72, v4
	v_add_f32_e32 v4, v12, v8
	v_add_f32_e32 v4, v9, v4
	v_add_f32_e32 v4, v13, v4
	v_add_f32_e32 v4, v10, v4
	v_add_f32_e32 v4, v14, v4
	v_add_f32_e32 v4, v11, v4
	v_add_f32_e32 v4, v15, v4
	v_add_f32_e32 v4, v66, v4
	v_add_f32_e32 v4, v67, v4
	v_fmamk_f32 v5, v81, 0x3e38aa3b, v139
	v_add_f32_e32 v4, v68, v4
	v_add_f32_e32 v4, v69, v4
	v_exp_f32_e32 v73, v5
	v_fmamk_f32 v5, v50, 0x3e38aa3b, v139
	v_add_f32_e32 v4, v70, v4
	v_exp_f32_e32 v50, v5
	v_fmamk_f32 v5, v51, 0x3e38aa3b, v139
	v_add_f32_e32 v4, v71, v4
	v_exp_f32_e32 v51, v5
	v_fmamk_f32 v5, v52, 0x3e38aa3b, v139
	v_add_f32_e32 v4, v72, v4
	v_exp_f32_e32 v52, v5
	v_fmamk_f32 v5, v53, 0x3e38aa3b, v139
	v_add_f32_e32 v4, v73, v4
	v_exp_f32_e32 v53, v5
	v_fmamk_f32 v5, v54, 0x3e38aa3b, v139
	v_add_f32_e32 v4, v50, v4
	v_exp_f32_e32 v54, v5
	v_fmamk_f32 v5, v55, 0x3e38aa3b, v139
	v_add_f32_e32 v4, v51, v4
	v_exp_f32_e32 v55, v5
	v_fmamk_f32 v5, v56, 0x3e38aa3b, v139
	v_add_f32_e32 v4, v52, v4
	v_exp_f32_e32 v56, v5
	v_fmamk_f32 v5, v57, 0x3e38aa3b, v139
	v_add_f32_e32 v4, v53, v4
	v_exp_f32_e32 v57, v5
	v_fmamk_f32 v5, v58, 0x3e38aa3b, v139
	v_add_f32_e32 v4, v54, v4
	v_exp_f32_e32 v58, v5
	v_fmamk_f32 v5, v59, 0x3e38aa3b, v139
	v_add_f32_e32 v4, v55, v4
	v_exp_f32_e32 v59, v5
	v_fmamk_f32 v5, v60, 0x3e38aa3b, v139
	v_add_f32_e32 v4, v56, v4
	v_exp_f32_e32 v60, v5
	v_add_f32_e32 v4, v57, v4
	v_add_f32_e32 v4, v58, v4
	v_add_f32_e32 v4, v59, v4
	v_sub_f32_e32 v2, v181, v138
	v_add_f32_e32 v74, v60, v4
	v_fmamk_f32 v4, v61, 0x3e38aa3b, v139
	v_exp_f32_e32 v2, v2
	v_exp_f32_e32 v61, v4
	ds_read_b64_tr_b16 v[4:5], v194 offset:8192
	ds_read_b64_tr_b16 v[6:7], v194 offset:9216
	v_cvt_pk_bf16_f32 v11, v11, v15
	v_cvt_pk_bf16_f32 v10, v10, v14
	v_cvt_pk_bf16_f32 v9, v9, v13
	v_cvt_pk_bf16_f32 v8, v8, v12
	ds_read_b64_tr_b16 v[14:15], v194 offset:9280
	ds_read_b64_tr_b16 v[12:13], v194 offset:8256
	s_cmp_eq_u64 s[100:101], 0
	s_cbranch_scc1 .Llz_selA
	v_pk_mul_f32 v[48:49], v[48:49], v[2:3] op_sel_hi:[1,0]
	v_pk_mul_f32 v[46:47], v[46:47], v[2:3] op_sel_hi:[1,0]
	v_pk_mul_f32 v[44:45], v[44:45], v[2:3] op_sel_hi:[1,0]
	v_pk_mul_f32 v[42:43], v[42:43], v[2:3] op_sel_hi:[1,0]
	v_pk_mul_f32 v[40:41], v[40:41], v[2:3] op_sel_hi:[1,0]
	v_pk_mul_f32 v[38:39], v[38:39], v[2:3] op_sel_hi:[1,0]
	v_pk_mul_f32 v[36:37], v[36:37], v[2:3] op_sel_hi:[1,0]
	v_pk_mul_f32 v[34:35], v[34:35], v[2:3] op_sel_hi:[1,0]
	v_pk_mul_f32 v[32:33], v[32:33], v[2:3] op_sel_hi:[1,0]
	v_pk_mul_f32 v[30:31], v[30:31], v[2:3] op_sel_hi:[1,0]
	v_pk_mul_f32 v[28:29], v[28:29], v[2:3] op_sel_hi:[1,0]
	v_pk_mul_f32 v[26:27], v[26:27], v[2:3] op_sel_hi:[1,0]
	v_pk_mul_f32 v[24:25], v[24:25], v[2:3] op_sel_hi:[1,0]
	v_pk_mul_f32 v[22:23], v[22:23], v[2:3] op_sel_hi:[1,0]
	v_pk_mul_f32 v[20:21], v[20:21], v[2:3] op_sel_hi:[1,0]
	v_pk_mul_f32 v[18:19], v[18:19], v[2:3] op_sel_hi:[1,0]

; DI float fexp2(float x) { return __builtin_amdgcn_exp2f(x); }
; DI f32x16 mfma32(bf16x8 a, bf16x8 b, f32x16 c) { return __builtin_amdgcn_mfma_f32_32x32x16_bf16(a, b, c, 0, 0, 0); }
; template <int MASK, bool NEAR, int PASS>
; DI void flash_tile(Flash& st, const bf16x8 (&qf)[4], const char* kbuf, const char* vbuf, int pos0, int qpos, bool on,
;                    const float* lut, float bfar, float* imp_row, float rinv) {
;     ...
; #pragma unroll
;     for (int ks = 0; ks < 4; ++ks) {
;         const int ka = r * 128 + (((2 * ks + h) ^ ((r >> 1) & 7)) << 4);
;         const bf16x8 a0 = *(const bf16x8*)(kbuf + ka);
;         const bf16x8 a1 = *(const bf16x8*)(kbuf + 4096 + ka);
;         s[0] = mfma32(a0, qf[ks], s[0]);
;         s[1] = mfma32(a1, qf[ks], s[1]);
;     }
;     constexpr float c1 = 0.125f * LOG2E;
;     float alpha = 1.f;
;     float rs = 0.f;
;     if (!NEAR) {
;         const float bc = MASK == 2 ? 0.f : bfar;
;         float mref;
;         if (PASS != 2) {
;             float mr = s[0][0];
; #pragma unroll
;             for (int i = 1; i < 16; ++i) mr = fmaxf(mr, s[0][i]);
; #pragma unroll
;             for (int i = 0; i < 16; ++i) mr = fmaxf(mr, s[1][i]);
;             float mx = on ? mr * c1 + bc : -1e30f;
;             mx = fmaxf(mx, __shfl_xor(mx, 32));
;             const float mnew = fmaxf(st.m, mx);
;             alpha = fexp2(st.m - mnew);
;             st.m = mnew;
;             mref = mnew;
;         } else mref = st.m;
;         float bm = on ? bc - mref : -1e30f;
;         if (PASS == 2) bm = on ? bm + __log2f(rinv) : -1e30f;
; #pragma unroll
;         for (int tt = 0; tt < 2; ++tt)
; #pragma unroll
;             for (int i = 0; i < 16; ++i) { const float pv = fexp2(s[tt][i] * c1 + bm); s[tt][i] = pv; rs += pv; }
;     DI bool operator()(int pos0) const {
;         if (kind == 0) return qvalid;
;         if (kind == 1) { const int blk = pos0 >> 8; return qvalid && (blk == cur || ((lo >> blk) & 1ull)); }
;         const int j = pos0 >> 6;
;         if (j >= 128) return qvalid;
;         const unsigned long long x = j < 64 ? lo : hi;
;         return qvalid && ((x >> (j & 63)) & 1ull) != 0ull;
;     }
.LBB0_1375:
	s_ashr_i32 s2, s22, 6
	s_cmpk_gt_i32 s2, 0x7f
	s_cselect_b64 vcc, -1, 0
	s_cmp_lt_i32 s2, 64
	s_cselect_b64 s[0:1], -1, 0
	v_cndmask_b32_e64 v5, v1, v157, s[0:1]
	v_cndmask_b32_e64 v4, v154, v174, s[0:1]
	v_lshrrev_b64 v[4:5], s2, v[4:5]
	v_and_b32_e32 v2, 1, v4
	v_cmp_eq_u32_e64 s[0:1], 1, v2
	s_and_b64 s[0:1], s[8:9], s[0:1]
	s_nop 0
	v_cndmask_b32_e64 v2, 0, 1, s[0:1]
	v_cndmask_b32_e32 v2, v2, v180, vcc
	v_and_b32_e32 v2, 1, v2
	v_cmp_eq_u32_e64 s[0:1], 1, v2
	v_cmp_ne_u32_e32 vcc, 0, v2
	s_cbranch_vccz .LBB0_1363
	ds_read_b128 v[50:53], v190 offset:16384
	ds_read_b128 v[138:141], v190 offset:20480
	ds_read_b128 v[150:153], v191 offset:16384
	ds_read_b128 v[12:15], v191 offset:20480
	ds_read_b128 v[146:149], v192 offset:16384
	ds_read_b128 v[8:11], v192 offset:20480
	ds_read_b128 v[142:145], v193 offset:16384
	ds_read_b128 v[4:7], v193 offset:20480
	s_add_i32 s2, s22, 0xb0
	v_cmp_le_i32_e32 vcc, s2, v226
	s_and_saveexec_b64 s[2:3], vcc
	s_xor_b64 s[2:3], exec, s[2:3]
	s_cbranch_execz .LBB0_1378
	s_waitcnt lgkmcnt(7)
	v_mfma_f32_32x32x16_bf16 v[66:81], v[50:53], v[94:97], 0
	s_waitcnt lgkmcnt(5)
	v_mfma_f32_32x32x16_bf16 v[66:81], v[150:153], v[98:101], v[66:81]
	v_mfma_f32_32x32x16_bf16 v[50:65], v[138:141], v[94:97], 0
	s_waitcnt lgkmcnt(3)
	v_mfma_f32_32x32x16_bf16 v[66:81], v[146:149], v[102:105], v[66:81]
	v_mfma_f32_32x32x16_bf16 v[50:65], v[12:15], v[98:101], v[50:65]
	s_waitcnt lgkmcnt(1)
	v_mfma_f32_32x32x16_bf16 v[66:81], v[142:145], v[106:109], v[66:81]
	v_mfma_f32_32x32x16_bf16 v[50:65], v[8:11], v[102:105], v[50:65]
	s_nop 10
	v_max3_f32 v2, v66, v67, v68
	v_max_f32_e32 v2, v2, v69
	v_max3_f32 v2, v2, v70, v71
	v_max3_f32 v2, v2, v72, v73
	v_max3_f32 v2, v2, v74, v75
	s_waitcnt lgkmcnt(0)
	v_mfma_f32_32x32x16_bf16 v[50:65], v[4:7], v[106:109], v[50:65]
	v_max3_f32 v2, v2, v76, v77
	v_max3_f32 v2, v2, v78, v79
	v_max3_f32 v2, v2, v80, v81
	s_nop 8
	v_max3_f32 v2, v2, v50, v51
	v_max3_f32 v2, v2, v52, v53
	v_max3_f32 v2, v2, v54, v55
	v_max3_f32 v2, v2, v56, v57
	v_max3_f32 v2, v2, v58, v59
	v_max3_f32 v2, v2, v60, v61
	v_max3_f32 v2, v2, v62, v63
	v_max3_f32 v2, v2, v64, v65
	v_fmamk_f32 v2, v2, 0x3e38aa3b, v225
	v_cndmask_b32_e64 v2, v215, v2, s[0:1]
	v_mov_b32_e32 v4, v2
	s_nop 1
	v_permlane32_swap_b32_e32 v2, v4
	v_max3_f32 v16, v181, v2, v4
	v_sub_f32_e32 v4, v16, v181
	v_cmp_lt_f32_e32 vcc, 0x41000000, v4
	s_nop 1
	v_cndmask_b32_e32 v16, v181, v16, vcc
	s_mov_b64 s[100:101], vcc
	v_sub_f32_e32 v4, v225, v16
	v_cndmask_b32_e64 v17, v215, v4, s[0:1]
	v_fmamk_f32 v4, v66, 0x3e38aa3b, v17
	v_exp_f32_e32 v8, v4
	v_fmamk_f32 v4, v67, 0x3e38aa3b, v17
	v_exp_f32_e32 v12, v4
	v_fmamk_f32 v4, v68, 0x3e38aa3b, v17
	v_exp_f32_e32 v9, v4
	v_fmamk_f32 v4, v69, 0x3e38aa3b, v17
	v_exp_f32_e32 v13, v4
	v_fmamk_f32 v4, v70, 0x3e38aa3b, v17
	v_exp_f32_e32 v10, v4
	v_fmamk_f32 v4, v71, 0x3e38aa3b, v17
	v_exp_f32_e32 v14, v4
	v_fmamk_f32 v4, v72, 0x3e38aa3b, v17
	v_exp_f32_e32 v11, v4
	v_fmamk_f32 v4, v73, 0x3e38aa3b, v17
	v_exp_f32_e32 v15, v4
	v_fmamk_f32 v4, v74, 0x3e38aa3b, v17
	v_exp_f32_e32 v66, v4
	v_fmamk_f32 v4, v75, 0x3e38aa3b, v17
	v_exp_f32_e32 v67, v4
	v_fmamk_f32 v4, v76, 0x3e38aa3b, v17
	v_exp_f32_e32 v68, v4
	v_fmamk_f32 v4, v77, 0x3e38aa3b, v17
	v_exp_f32_e32 v69, v4
	v_fmamk_f32 v4, v78, 0x3e38aa3b, v17
	v_exp_f32_e32 v70, v4
	v_fmamk_f32 v4, v79, 0x3e38aa3b, v17
	v_exp_f32_e32 v71, v4
	v_fmamk_f32 v4, v80, 0x3e38aa3b, v17
	v_exp_f32_e32 v72, v4
	v_add_f32_e32 v4, v12, v8
	v_add_f32_e32 v4, v9, v4
	v_add_f32_e32 v4, v13, v4
	v_add_f32_e32 v4, v10, v4
	v_add_f32_e32 v4, v14, v4
	v_add_f32_e32 v4, v11, v4
	v_add_f32_e32 v4, v15, v4
	v_add_f32_e32 v4, v66, v4
	v_add_f32_e32 v4, v67, v4
	v_fmamk_f32 v5, v81, 0x3e38aa3b, v17
	v_add_f32_e32 v4, v68, v4
	v_add_f32_e32 v4, v69, v4
	v_exp_f32_e32 v73, v5
	v_fmamk_f32 v5, v50, 0x3e38aa3b, v17
	v_add_f32_e32 v4, v70, v4
	v_exp_f32_e32 v50, v5
	v_fmamk_f32 v5, v51, 0x3e38aa3b, v17
	v_add_f32_e32 v4, v71, v4
	v_exp_f32_e32 v51, v5
	v_fmamk_f32 v5, v52, 0x3e38aa3b, v17
	v_add_f32_e32 v4, v72, v4
	v_exp_f32_e32 v52, v5
	v_fmamk_f32 v5, v53, 0x3e38aa3b, v17
	v_add_f32_e32 v4, v73, v4
	v_exp_f32_e32 v53, v5
	v_fmamk_f32 v5, v54, 0x3e38aa3b, v17
	v_add_f32_e32 v4, v50, v4
	v_exp_f32_e32 v54, v5
	v_fmamk_f32 v5, v55, 0x3e38aa3b, v17
	v_add_f32_e32 v4, v51, v4
	v_exp_f32_e32 v55, v5
	v_fmamk_f32 v5, v56, 0x3e38aa3b, v17
	v_add_f32_e32 v4, v52, v4
	v_exp_f32_e32 v56, v5
	v_fmamk_f32 v5, v57, 0x3e38aa3b, v17
	v_add_f32_e32 v4, v53, v4
	v_exp_f32_e32 v57, v5
	v_fmamk_f32 v5, v58, 0x3e38aa3b, v17
	v_add_f32_e32 v4, v54, v4
	v_exp_f32_e32 v58, v5
	v_fmamk_f32 v5, v59, 0x3e38aa3b, v17
	v_add_f32_e32 v4, v55, v4
	v_exp_f32_e32 v59, v5
	v_fmamk_f32 v5, v60, 0x3e38aa3b, v17
	v_add_f32_e32 v4, v56, v4
	v_exp_f32_e32 v60, v5
	v_add_f32_e32 v4, v57, v4
	v_add_f32_e32 v4, v58, v4
	v_add_f32_e32 v4, v59, v4
	v_sub_f32_e32 v2, v181, v16
	v_add_f32_e32 v74, v60, v4
	v_fmamk_f32 v4, v61, 0x3e38aa3b, v17
	v_exp_f32_e32 v2, v2
	v_exp_f32_e32 v61, v4
	ds_read_b64_tr_b16 v[4:5], v194 offset:24576
	ds_read_b64_tr_b16 v[6:7], v194 offset:25600
	v_cvt_pk_bf16_f32 v11, v11, v15
	v_cvt_pk_bf16_f32 v10, v10, v14
	v_cvt_pk_bf16_f32 v9, v9, v13
	v_cvt_pk_bf16_f32 v8, v8, v12
	ds_read_b64_tr_b16 v[14:15], v194 offset:25664
	ds_read_b64_tr_b16 v[12:13], v194 offset:24640
	s_cmp_eq_u64 s[100:101], 0
	s_cbranch_scc1 .Llz_selB
	v_pk_mul_f32 v[48:49], v[48:49], v[2:3] op_sel_hi:[1,0]
	v_pk_mul_f32 v[46:47], v[46:47], v[2:3] op_sel_hi:[1,0]
	v_pk_mul_f32 v[44:45], v[44:45], v[2:3] op_sel_hi:[1,0]
	v_pk_mul_f32 v[42:43], v[42:43], v[2:3] op_sel_hi:[1,0]
	v_pk_mul_f32 v[40:41], v[40:41], v[2:3] op_sel_hi:[1,0]
	v_pk_mul_f32 v[38:39], v[38:39], v[2:3] op_sel_hi:[1,0]
	v_pk_mul_f32 v[36:37], v[36:37], v[2:3] op_sel_hi:[1,0]
	v_pk_mul_f32 v[34:35], v[34:35], v[2:3] op_sel_hi:[1,0]
	v_pk_mul_f32 v[32:33], v[32:33], v[2:3] op_sel_hi:[1,0]
	v_pk_mul_f32 v[30:31], v[30:31], v[2:3] op_sel_hi:[1,0]
	v_pk_mul_f32 v[28:29], v[28:29], v[2:3] op_sel_hi:[1,0]
	v_pk_mul_f32 v[26:27], v[26:27], v[2:3] op_sel_hi:[1,0]
	v_pk_mul_f32 v[24:25], v[24:25], v[2:3] op_sel_hi:[1,0]
	v_pk_mul_f32 v[22:23], v[22:23], v[2:3] op_sel_hi:[1,0]
	v_pk_mul_f32 v[20:21], v[20:21], v[2:3] op_sel_hi:[1,0]
	v_pk_mul_f32 v[18:19], v[18:19], v[2:3] op_sel_hi:[1,0]

; DI float fexp2(float x) { return __builtin_amdgcn_exp2f(x); }
; DI f32x16 mfma32(bf16x8 a, bf16x8 b, f32x16 c) { return __builtin_amdgcn_mfma_f32_32x32x16_bf16(a, b, c, 0, 0, 0); }
; template <int MASK, bool NEAR, int PASS>
; DI void flash_tile(Flash& st, const bf16x8 (&qf)[4], const char* kbuf, const char* vbuf, int pos0, int qpos, bool on,
;                    const float* lut, float bfar, float* imp_row, float rinv) {
;     ...
; #pragma unroll
;     for (int ks = 0; ks < 4; ++ks) {
;         const int ka = r * 128 + (((2 * ks + h) ^ ((r >> 1) & 7)) << 4);
;         const bf16x8 a0 = *(const bf16x8*)(kbuf + ka);
;         const bf16x8 a1 = *(const bf16x8*)(kbuf + 4096 + ka);
;         s[0] = mfma32(a0, qf[ks], s[0]);
;         s[1] = mfma32(a1, qf[ks], s[1]);
;     }
;     constexpr float c1 = 0.125f * LOG2E;
;     float alpha = 1.f;
;     float rs = 0.f;
;     if (!NEAR) {
;         const float bc = MASK == 2 ? 0.f : bfar;
;         float mref;
;         if (PASS != 2) {
;             float mr = s[0][0];
; #pragma unroll
;             for (int i = 1; i < 16; ++i) mr = fmaxf(mr, s[0][i]);
; #pragma unroll
;             for (int i = 0; i < 16; ++i) mr = fmaxf(mr, s[1][i]);
;             float mx = on ? mr * c1 + bc : -1e30f;
;             mx = fmaxf(mx, __shfl_xor(mx, 32));
;             const float mnew = fmaxf(st.m, mx);
;             alpha = fexp2(st.m - mnew);
;             st.m = mnew;
;             mref = mnew;
;         } else mref = st.m;
;         float bm = on ? bc - mref : -1e30f;
;         if (PASS == 2) bm = on ? bm + __log2f(rinv) : -1e30f;
; #pragma unroll
;         for (int tt = 0; tt < 2; ++tt)
; #pragma unroll
;             for (int i = 0; i < 16; ++i) { const float pv = fexp2(s[tt][i] * c1 + bm); s[tt][i] = pv; rs += pv; }
.LBB0_1420:
	s_andn2_saveexec_b64 s[0:1], s[0:1]
	s_cbranch_execz .LBB0_1422
	s_waitcnt lgkmcnt(7)
	v_mfma_f32_32x32x16_bf16 v[66:81], v[50:53], v[94:97], 0
	s_waitcnt lgkmcnt(5)
	v_mfma_f32_32x32x16_bf16 v[66:81], v[150:153], v[98:101], v[66:81]
	v_mfma_f32_32x32x16_bf16 v[50:65], v[138:141], v[94:97], 0
	s_waitcnt lgkmcnt(3)
	v_mfma_f32_32x32x16_bf16 v[66:81], v[146:149], v[102:105], v[66:81]
	v_mfma_f32_32x32x16_bf16 v[50:65], v[12:15], v[98:101], v[50:65]
	s_waitcnt lgkmcnt(1)
	v_mfma_f32_32x32x16_bf16 v[66:81], v[142:145], v[106:109], v[66:81]
	v_mfma_f32_32x32x16_bf16 v[50:65], v[8:11], v[102:105], v[50:65]
	s_nop 10
	v_max_f32_e32 v2, v67, v67
	v_max_f32_e32 v12, v66, v66
	v_max_f32_e32 v2, v12, v2
	v_max3_f32 v2, v2, v68, v69
	v_max3_f32 v2, v2, v70, v71
	v_max3_f32 v2, v2, v72, v73
	v_max3_f32 v2, v2, v74, v75
	s_waitcnt lgkmcnt(0)
	v_mfma_f32_32x32x16_bf16 v[50:65], v[4:7], v[106:109], v[50:65]
	v_max3_f32 v2, v2, v76, v77
	v_max3_f32 v2, v2, v78, v79
	v_max3_f32 v2, v2, v80, v81
	s_nop 8
	v_max3_f32 v2, v2, v50, v51
	v_max3_f32 v2, v2, v52, v53
	v_max3_f32 v2, v2, v54, v55
	v_max3_f32 v2, v2, v56, v57
	v_max3_f32 v2, v2, v58, v59
	v_max3_f32 v2, v2, v60, v61
	v_max3_f32 v2, v2, v62, v63
	v_max3_f32 v2, v2, v64, v65
	v_fmamk_f32 v2, v2, 0x3e38aa3b, v225
	v_cndmask_b32_e64 v2, v215, v2, s[8:9]
	v_mov_b32_e32 v4, v2
	s_nop 1
	v_permlane32_swap_b32_e32 v2, v4
	v_max3_f32 v138, v173, v2, v4
	s_mov_b32 s99, 0x41000000
	v_sub_f32_e32 v4, v138, v173
	v_cmp_lt_f32_e64 s[100:101], s99, v4
	s_nop 1
	v_cndmask_b32_e64 v138, v173, v138, s[100:101]
	v_sub_f32_e32 v4, v225, v138
	v_cndmask_b32_e64 v139, v215, v4, s[8:9]
	v_fmamk_f32 v4, v66, 0x3e38aa3b, v139
	v_exp_f32_e32 v8, v4
	v_fmamk_f32 v4, v67, 0x3e38aa3b, v139
	v_exp_f32_e32 v12, v4
	v_fmamk_f32 v4, v68, 0x3e38aa3b, v139
	v_exp_f32_e32 v9, v4
	v_fmamk_f32 v4, v69, 0x3e38aa3b, v139
	v_exp_f32_e32 v13, v4
	v_fmamk_f32 v4, v70, 0x3e38aa3b, v139
	v_exp_f32_e32 v10, v4
	v_fmamk_f32 v4, v71, 0x3e38aa3b, v139
	v_exp_f32_e32 v14, v4
	v_fmamk_f32 v4, v72, 0x3e38aa3b, v139
	v_exp_f32_e32 v11, v4
	v_fmamk_f32 v4, v73, 0x3e38aa3b, v139
	v_exp_f32_e32 v15, v4
	v_fmamk_f32 v4, v74, 0x3e38aa3b, v139
	v_exp_f32_e32 v66, v4
	v_fmamk_f32 v4, v75, 0x3e38aa3b, v139
	v_exp_f32_e32 v67, v4
	v_fmamk_f32 v4, v76, 0x3e38aa3b, v139
	v_exp_f32_e32 v68, v4
	v_fmamk_f32 v4, v77, 0x3e38aa3b, v139
	v_exp_f32_e32 v69, v4
	v_fmamk_f32 v4, v78, 0x3e38aa3b, v139
	v_exp_f32_e32 v70, v4
	v_fmamk_f32 v4, v79, 0x3e38aa3b, v139
	v_exp_f32_e32 v71, v4
	v_fmamk_f32 v4, v80, 0x3e38aa3b, v139
	v_exp_f32_e32 v72, v4
	v_add_f32_e32 v4, 0, v8
	v_add_f32_e32 v4, v12, v4
	v_add_f32_e32 v4, v9, v4
	v_add_f32_e32 v4, v13, v4
	v_add_f32_e32 v4, v10, v4
	v_add_f32_e32 v4, v14, v4
	v_add_f32_e32 v4, v11, v4
	v_add_f32_e32 v4, v15, v4
	v_add_f32_e32 v4, v66, v4
	v_add_f32_e32 v4, v67, v4
	v_fmamk_f32 v5, v81, 0x3e38aa3b, v139
	v_add_f32_e32 v4, v68, v4
	v_add_f32_e32 v4, v69, v4
	v_exp_f32_e32 v73, v5
	v_fmamk_f32 v5, v50, 0x3e38aa3b, v139
	v_add_f32_e32 v4, v70, v4
	v_exp_f32_e32 v50, v5
	v_fmamk_f32 v5, v51, 0x3e38aa3b, v139
	v_add_f32_e32 v4, v71, v4
	v_exp_f32_e32 v51, v5
	v_fmamk_f32 v5, v52, 0x3e38aa3b, v139
	v_add_f32_e32 v4, v72, v4
	v_exp_f32_e32 v52, v5
	v_fmamk_f32 v5, v53, 0x3e38aa3b, v139
	v_add_f32_e32 v4, v73, v4
	v_exp_f32_e32 v53, v5
	v_fmamk_f32 v5, v54, 0x3e38aa3b, v139
	v_add_f32_e32 v4, v50, v4
	v_exp_f32_e32 v54, v5
	v_fmamk_f32 v5, v55, 0x3e38aa3b, v139
	v_add_f32_e32 v4, v51, v4
	v_exp_f32_e32 v55, v5
	v_fmamk_f32 v5, v56, 0x3e38aa3b, v139
	v_add_f32_e32 v4, v52, v4
	v_exp_f32_e32 v56, v5
	v_fmamk_f32 v5, v57, 0x3e38aa3b, v139
	v_add_f32_e32 v4, v53, v4
	v_exp_f32_e32 v57, v5
	v_fmamk_f32 v5, v58, 0x3e38aa3b, v139
	v_add_f32_e32 v4, v54, v4
	v_exp_f32_e32 v58, v5
	v_fmamk_f32 v5, v59, 0x3e38aa3b, v139
	v_add_f32_e32 v4, v55, v4
	v_exp_f32_e32 v59, v5
	v_fmamk_f32 v5, v60, 0x3e38aa3b, v139
	v_add_f32_e32 v4, v56, v4
	v_exp_f32_e32 v60, v5
	v_add_f32_e32 v4, v57, v4
	v_add_f32_e32 v4, v58, v4
	v_add_f32_e32 v4, v59, v4
	v_sub_f32_e32 v2, v173, v138
	v_add_f32_e32 v74, v60, v4
	v_fmamk_f32 v4, v61, 0x3e38aa3b, v139
	v_exp_f32_e32 v2, v2
	v_exp_f32_e32 v61, v4
	ds_read_b64_tr_b16 v[4:5], v194 offset:8192
	ds_read_b64_tr_b16 v[6:7], v194 offset:9216
	v_cvt_pk_bf16_f32 v11, v11, v15
	v_cvt_pk_bf16_f32 v10, v10, v14
	v_cvt_pk_bf16_f32 v9, v9, v13
	v_cvt_pk_bf16_f32 v8, v8, v12
	ds_read_b64_tr_b16 v[14:15], v194 offset:9280
	ds_read_b64_tr_b16 v[12:13], v194 offset:8256
	s_cmp_eq_u64 s[100:101], 0
	s_cbranch_scc1 .Llz_winA
	v_pk_mul_f32 v[48:49], v[48:49], v[2:3] op_sel_hi:[1,0]
	v_pk_mul_f32 v[46:47], v[46:47], v[2:3] op_sel_hi:[1,0]
	v_pk_mul_f32 v[44:45], v[44:45], v[2:3] op_sel_hi:[1,0]
	v_pk_mul_f32 v[42:43], v[42:43], v[2:3] op_sel_hi:[1,0]
	v_pk_mul_f32 v[40:41], v[40:41], v[2:3] op_sel_hi:[1,0]
	v_pk_mul_f32 v[38:39], v[38:39], v[2:3] op_sel_hi:[1,0]
	v_pk_mul_f32 v[36:37], v[36:37], v[2:3] op_sel_hi:[1,0]
	v_pk_mul_f32 v[34:35], v[34:35], v[2:3] op_sel_hi:[1,0]
	v_pk_mul_f32 v[32:33], v[32:33], v[2:3] op_sel_hi:[1,0]
	v_pk_mul_f32 v[30:31], v[30:31], v[2:3] op_sel_hi:[1,0]
	v_pk_mul_f32 v[28:29], v[28:29], v[2:3] op_sel_hi:[1,0]
	v_pk_mul_f32 v[26:27], v[26:27], v[2:3] op_sel_hi:[1,0]
	v_pk_mul_f32 v[24:25], v[24:25], v[2:3] op_sel_hi:[1,0]
	v_pk_mul_f32 v[22:23], v[22:23], v[2:3] op_sel_hi:[1,0]
	v_pk_mul_f32 v[20:21], v[20:21], v[2:3] op_sel_hi:[1,0]
	v_pk_mul_f32 v[18:19], v[18:19], v[2:3] op_sel_hi:[1,0]
	s_nop 1

; DI float fexp2(float x) { return __builtin_amdgcn_exp2f(x); }
; DI f32x16 mfma32(bf16x8 a, bf16x8 b, f32x16 c) { return __builtin_amdgcn_mfma_f32_32x32x16_bf16(a, b, c, 0, 0, 0); }
; template <int MASK, bool NEAR, int PASS>
; DI void flash_tile(Flash& st, const bf16x8 (&qf)[4], const char* kbuf, const char* vbuf, int pos0, int qpos, bool on,
;                    const float* lut, float bfar, float* imp_row, float rinv) {
;     ...
; #pragma unroll
;     for (int ks = 0; ks < 4; ++ks) {
;         const int ka = r * 128 + (((2 * ks + h) ^ ((r >> 1) & 7)) << 4);
;         const bf16x8 a0 = *(const bf16x8*)(kbuf + ka);
;         const bf16x8 a1 = *(const bf16x8*)(kbuf + 4096 + ka);
;         s[0] = mfma32(a0, qf[ks], s[0]);
;         s[1] = mfma32(a1, qf[ks], s[1]);
;     }
;     constexpr float c1 = 0.125f * LOG2E;
;     float alpha = 1.f;
;     float rs = 0.f;
;     if (!NEAR) {
;         const float bc = MASK == 2 ? 0.f : bfar;
;         float mref;
;         if (PASS != 2) {
;             float mr = s[0][0];
; #pragma unroll
;             for (int i = 1; i < 16; ++i) mr = fmaxf(mr, s[0][i]);
; #pragma unroll
;             for (int i = 0; i < 16; ++i) mr = fmaxf(mr, s[1][i]);
;             float mx = on ? mr * c1 + bc : -1e30f;
;             mx = fmaxf(mx, __shfl_xor(mx, 32));
;             const float mnew = fmaxf(st.m, mx);
;             alpha = fexp2(st.m - mnew);
;             st.m = mnew;
;             mref = mnew;
;         } else mref = st.m;
;         float bm = on ? bc - mref : -1e30f;
;         if (PASS == 2) bm = on ? bm + __log2f(rinv) : -1e30f;
; #pragma unroll
;         for (int tt = 0; tt < 2; ++tt)
; #pragma unroll
;             for (int i = 0; i < 16; ++i) { const float pv = fexp2(s[tt][i] * c1 + bm); s[tt][i] = pv; rs += pv; }
.LBB0_1429:
	s_andn2_saveexec_b64 s[0:1], s[0:1]
	s_cbranch_execz .LBB0_1413
	s_waitcnt lgkmcnt(7)
	v_mfma_f32_32x32x16_bf16 v[66:81], v[50:53], v[94:97], 0
	s_waitcnt lgkmcnt(5)
	v_mfma_f32_32x32x16_bf16 v[66:81], v[150:153], v[98:101], v[66:81]
	v_mfma_f32_32x32x16_bf16 v[50:65], v[138:141], v[94:97], 0
	s_waitcnt lgkmcnt(3)
	v_mfma_f32_32x32x16_bf16 v[66:81], v[146:149], v[102:105], v[66:81]
	v_mfma_f32_32x32x16_bf16 v[50:65], v[12:15], v[98:101], v[50:65]
	s_waitcnt lgkmcnt(1)
	v_mfma_f32_32x32x16_bf16 v[66:81], v[142:145], v[106:109], v[66:81]
	v_mfma_f32_32x32x16_bf16 v[50:65], v[8:11], v[102:105], v[50:65]
	s_nop 10
	v_max_f32_e32 v2, v67, v67
	v_max_f32_e32 v12, v66, v66
	v_max_f32_e32 v2, v12, v2
	v_max3_f32 v2, v2, v68, v69
	v_max3_f32 v2, v2, v70, v71
	v_max3_f32 v2, v2, v72, v73
	v_max3_f32 v2, v2, v74, v75
	s_waitcnt lgkmcnt(0)
	v_mfma_f32_32x32x16_bf16 v[50:65], v[4:7], v[106:109], v[50:65]
	v_max3_f32 v2, v2, v76, v77
	v_max3_f32 v2, v2, v78, v79
	v_max3_f32 v2, v2, v80, v81
	s_nop 8
	v_max3_f32 v2, v2, v50, v51
	v_max3_f32 v2, v2, v52, v53
	v_max3_f32 v2, v2, v54, v55
	v_max3_f32 v2, v2, v56, v57
	v_max3_f32 v2, v2, v58, v59
	v_max3_f32 v2, v2, v60, v61
	v_max3_f32 v2, v2, v62, v63
	v_max3_f32 v2, v2, v64, v65
	v_fmamk_f32 v2, v2, 0x3e38aa3b, v225
	v_cndmask_b32_e64 v2, v215, v2, s[8:9]
	v_mov_b32_e32 v4, v2
	s_nop 1
	v_permlane32_swap_b32_e32 v2, v4
	v_max3_f32 v16, v173, v2, v4
	s_mov_b32 s99, 0x41000000
	v_sub_f32_e32 v4, v16, v173
	v_cmp_lt_f32_e64 s[100:101], s99, v4
	s_nop 1
	v_cndmask_b32_e64 v16, v173, v16, s[100:101]
	v_sub_f32_e32 v4, v225, v16
	v_cndmask_b32_e64 v17, v215, v4, s[8:9]
	v_fmamk_f32 v4, v66, 0x3e38aa3b, v17
	v_exp_f32_e32 v8, v4
	v_fmamk_f32 v4, v67, 0x3e38aa3b, v17
	v_exp_f32_e32 v12, v4
	v_fmamk_f32 v4, v68, 0x3e38aa3b, v17
	v_exp_f32_e32 v9, v4
	v_fmamk_f32 v4, v69, 0x3e38aa3b, v17
	v_exp_f32_e32 v13, v4
	v_fmamk_f32 v4, v70, 0x3e38aa3b, v17
	v_exp_f32_e32 v10, v4
	v_fmamk_f32 v4, v71, 0x3e38aa3b, v17
	v_exp_f32_e32 v14, v4
	v_fmamk_f32 v4, v72, 0x3e38aa3b, v17
	v_exp_f32_e32 v11, v4
	v_fmamk_f32 v4, v73, 0x3e38aa3b, v17
	v_exp_f32_e32 v15, v4
	v_fmamk_f32 v4, v74, 0x3e38aa3b, v17
	v_exp_f32_e32 v66, v4
	v_fmamk_f32 v4, v75, 0x3e38aa3b, v17
	v_exp_f32_e32 v67, v4
	v_fmamk_f32 v4, v76, 0x3e38aa3b, v17
	v_exp_f32_e32 v68, v4
	v_fmamk_f32 v4, v77, 0x3e38aa3b, v17
	v_exp_f32_e32 v69, v4
	v_fmamk_f32 v4, v78, 0x3e38aa3b, v17
	v_exp_f32_e32 v70, v4
	v_fmamk_f32 v4, v79, 0x3e38aa3b, v17
	v_exp_f32_e32 v71, v4
	v_fmamk_f32 v4, v80, 0x3e38aa3b, v17
	v_exp_f32_e32 v72, v4
	v_add_f32_e32 v4, 0, v8
	v_add_f32_e32 v4, v12, v4
	v_add_f32_e32 v4, v9, v4
	v_add_f32_e32 v4, v13, v4
	v_add_f32_e32 v4, v10, v4
	v_add_f32_e32 v4, v14, v4
	v_add_f32_e32 v4, v11, v4
	v_add_f32_e32 v4, v15, v4
	v_add_f32_e32 v4, v66, v4
	v_add_f32_e32 v4, v67, v4
	v_fmamk_f32 v5, v81, 0x3e38aa3b, v17
	v_add_f32_e32 v4, v68, v4
	v_add_f32_e32 v4, v69, v4
	v_exp_f32_e32 v73, v5
	v_fmamk_f32 v5, v50, 0x3e38aa3b, v17
	v_add_f32_e32 v4, v70, v4
	v_exp_f32_e32 v50, v5
	v_fmamk_f32 v5, v51, 0x3e38aa3b, v17
	v_add_f32_e32 v4, v71, v4
	v_exp_f32_e32 v51, v5
	v_fmamk_f32 v5, v52, 0x3e38aa3b, v17
	v_add_f32_e32 v4, v72, v4
	v_exp_f32_e32 v52, v5
	v_fmamk_f32 v5, v53, 0x3e38aa3b, v17
	v_add_f32_e32 v4, v73, v4
	v_exp_f32_e32 v53, v5
	v_fmamk_f32 v5, v54, 0x3e38aa3b, v17
	v_add_f32_e32 v4, v50, v4
	v_exp_f32_e32 v54, v5
	v_fmamk_f32 v5, v55, 0x3e38aa3b, v17
	v_add_f32_e32 v4, v51, v4
	v_exp_f32_e32 v55, v5
	v_fmamk_f32 v5, v56, 0x3e38aa3b, v17
	v_add_f32_e32 v4, v52, v4
	v_exp_f32_e32 v56, v5
	v_fmamk_f32 v5, v57, 0x3e38aa3b, v17
	v_add_f32_e32 v4, v53, v4
	v_exp_f32_e32 v57, v5
	v_fmamk_f32 v5, v58, 0x3e38aa3b, v17
	v_add_f32_e32 v4, v54, v4
	v_exp_f32_e32 v58, v5
	v_fmamk_f32 v5, v59, 0x3e38aa3b, v17
	v_add_f32_e32 v4, v55, v4
	v_exp_f32_e32 v59, v5
	v_fmamk_f32 v5, v60, 0x3e38aa3b, v17
	v_add_f32_e32 v4, v56, v4
	v_exp_f32_e32 v60, v5
	v_add_f32_e32 v4, v57, v4
	v_add_f32_e32 v4, v58, v4
	v_add_f32_e32 v4, v59, v4
	v_sub_f32_e32 v2, v173, v16
	v_add_f32_e32 v74, v60, v4
	v_fmamk_f32 v4, v61, 0x3e38aa3b, v17
	v_exp_f32_e32 v2, v2
	v_exp_f32_e32 v61, v4
	ds_read_b64_tr_b16 v[4:5], v194 offset:24576
	ds_read_b64_tr_b16 v[6:7], v194 offset:25600
	v_cvt_pk_bf16_f32 v11, v11, v15
	v_cvt_pk_bf16_f32 v10, v10, v14
	v_cvt_pk_bf16_f32 v9, v9, v13
	v_cvt_pk_bf16_f32 v8, v8, v12
	ds_read_b64_tr_b16 v[14:15], v194 offset:25664
	ds_read_b64_tr_b16 v[12:13], v194 offset:24640
	s_cmp_eq_u64 s[100:101], 0
	s_cbranch_scc1 .Llz_winB
	v_pk_mul_f32 v[48:49], v[48:49], v[2:3] op_sel_hi:[1,0]
	v_pk_mul_f32 v[46:47], v[46:47], v[2:3] op_sel_hi:[1,0]
	v_pk_mul_f32 v[44:45], v[44:45], v[2:3] op_sel_hi:[1,0]
	v_pk_mul_f32 v[42:43], v[42:43], v[2:3] op_sel_hi:[1,0]
	v_pk_mul_f32 v[40:41], v[40:41], v[2:3] op_sel_hi:[1,0]
	v_pk_mul_f32 v[38:39], v[38:39], v[2:3] op_sel_hi:[1,0]
	v_pk_mul_f32 v[36:37], v[36:37], v[2:3] op_sel_hi:[1,0]
	v_pk_mul_f32 v[34:35], v[34:35], v[2:3] op_sel_hi:[1,0]
	v_pk_mul_f32 v[32:33], v[32:33], v[2:3] op_sel_hi:[1,0]
	v_pk_mul_f32 v[30:31], v[30:31], v[2:3] op_sel_hi:[1,0]
	v_pk_mul_f32 v[28:29], v[28:29], v[2:3] op_sel_hi:[1,0]
	v_pk_mul_f32 v[26:27], v[26:27], v[2:3] op_sel_hi:[1,0]
	v_pk_mul_f32 v[24:25], v[24:25], v[2:3] op_sel_hi:[1,0]
	v_pk_mul_f32 v[22:23], v[22:23], v[2:3] op_sel_hi:[1,0]
	v_pk_mul_f32 v[20:21], v[20:21], v[2:3] op_sel_hi:[1,0]
	v_pk_mul_f32 v[18:19], v[18:19], v[2:3] op_sel_hi:[1,0]
	s_nop 1

; DI float fexp2(float x) { return __builtin_amdgcn_exp2f(x); }
; DI f32x16 mfma32(bf16x8 a, bf16x8 b, f32x16 c) { return __builtin_amdgcn_mfma_f32_32x32x16_bf16(a, b, c, 0, 0, 0); }
; template <int MASK, bool NEAR, int PASS>
; DI void flash_tile(Flash& st, const bf16x8 (&qf)[4], const char* kbuf, const char* vbuf, int pos0, int qpos, bool on,
;                    const float* lut, float bfar, float* imp_row, float rinv) {
;     ...
; #pragma unroll
;     for (int ks = 0; ks < 4; ++ks) {
;         const int ka = r * 128 + (((2 * ks + h) ^ ((r >> 1) & 7)) << 4);
;         const bf16x8 a0 = *(const bf16x8*)(kbuf + ka);
;         const bf16x8 a1 = *(const bf16x8*)(kbuf + 4096 + ka);
;         s[0] = mfma32(a0, qf[ks], s[0]);
;         s[1] = mfma32(a1, qf[ks], s[1]);
;     }
;     constexpr float c1 = 0.125f * LOG2E;
;     float alpha = 1.f;
;     float rs = 0.f;
;     if (!NEAR) {
;         const float bc = MASK == 2 ? 0.f : bfar;
;         float mref;
;         if (PASS != 2) {
;             float mr = s[0][0];
; #pragma unroll
;             for (int i = 1; i < 16; ++i) mr = fmaxf(mr, s[0][i]);
; #pragma unroll
;             for (int i = 0; i < 16; ++i) mr = fmaxf(mr, s[1][i]);
;             float mx = on ? mr * c1 + bc : -1e30f;
;             mx = fmaxf(mx, __shfl_xor(mx, 32));
;             const float mnew = fmaxf(st.m, mx);
;             alpha = fexp2(st.m - mnew);
;             st.m = mnew;
;             mref = mnew;
;         } else mref = st.m;
;         float bm = on ? bc - mref : -1e30f;
;         if (PASS == 2) bm = on ? bm + __log2f(rinv) : -1e30f;
; #pragma unroll
;         for (int tt = 0; tt < 2; ++tt)
; #pragma unroll
;             for (int i = 0; i < 16; ++i) { const float pv = fexp2(s[tt][i] * c1 + bm); s[tt][i] = pv; rs += pv; }
.LBB0_1522:
	s_cmp_eq_u64 exec, 0
	s_cbranch_scc1 .LBB0_1528
	v_add_u32_e32 v2, 0, v190
	ds_read_b128 v[50:53], v2
	ds_read_b128 v[130:133], v2 offset:4096
	v_add_u32_e32 v2, 0, v191
	ds_read_b128 v[142:145], v2
	ds_read_b128 v[12:15], v2 offset:4096
	v_add_u32_e32 v2, 0, v192
	ds_read_b128 v[138:141], v2
	ds_read_b128 v[8:11], v2 offset:4096
	v_add_u32_e32 v2, 0, v193
	ds_read_b128 v[134:137], v2
	ds_read_b128 v[4:7], v2 offset:4096
	s_waitcnt lgkmcnt(8)
	v_add_u32_e32 v2, 0xb0, v66
	v_cmp_le_i32_e32 vcc, v2, v158
	s_and_saveexec_b64 s[2:3], vcc
	s_xor_b64 s[2:3], exec, s[2:3]
	s_cbranch_execz .LBB0_1525
	s_waitcnt lgkmcnt(7)
	v_mfma_f32_32x32x16_bf16 v[66:81], v[50:53], v[82:85], 0
	s_waitcnt lgkmcnt(5)
	v_mfma_f32_32x32x16_bf16 v[66:81], v[142:145], v[86:89], v[66:81]
	v_mfma_f32_32x32x16_bf16 v[50:65], v[130:133], v[82:85], 0
	s_waitcnt lgkmcnt(3)
	v_mfma_f32_32x32x16_bf16 v[66:81], v[138:141], v[90:93], v[66:81]
	v_mfma_f32_32x32x16_bf16 v[50:65], v[12:15], v[86:89], v[50:65]
	s_waitcnt lgkmcnt(1)
	v_mfma_f32_32x32x16_bf16 v[66:81], v[134:137], v[94:97], v[66:81]
	v_mfma_f32_32x32x16_bf16 v[50:65], v[8:11], v[90:93], v[50:65]
	s_nop 10
	v_max_f32_e32 v2, v67, v67
	v_max_f32_e32 v12, v66, v66
	v_max_f32_e32 v2, v12, v2
	v_max3_f32 v2, v2, v68, v69
	v_max3_f32 v2, v2, v70, v71
	v_max3_f32 v2, v2, v72, v73
	v_max3_f32 v2, v2, v74, v75
	s_waitcnt lgkmcnt(0)
	v_mfma_f32_32x32x16_bf16 v[50:65], v[4:7], v[94:97], v[50:65]
	v_max3_f32 v2, v2, v76, v77
	v_max3_f32 v2, v2, v78, v79
	v_max3_f32 v2, v2, v80, v81
	v_and_b32_e32 v5, 64, v188
	v_xor_b32_e32 v4, 32, v188
	v_add_u32_e32 v5, 64, v5
	v_cmp_lt_i32_e32 vcc, v4, v5
	s_nop 4
	v_max3_f32 v2, v2, v50, v51
	v_max3_f32 v2, v2, v52, v53
	v_max3_f32 v2, v2, v54, v55
	v_max3_f32 v2, v2, v56, v57
	v_max3_f32 v2, v2, v58, v59
	v_max3_f32 v2, v2, v60, v61
	v_max3_f32 v2, v2, v62, v63
	v_max3_f32 v2, v2, v64, v65
	v_cndmask_b32_e32 v4, v188, v4, vcc
	v_fmamk_f32 v2, v2, 0x3e38aa3b, v162
	v_lshlrev_b32_e32 v130, 2, v4
	v_mov_b32_e32 v4, v2
	s_nop 1
	v_permlane32_swap_b32_e32 v2, v4
	v_max3_f32 v131, v165, v2, v4
	s_mov_b32 s99, 0x41000000
	v_sub_f32_e32 v4, v131, v165
	v_cmp_lt_f32_e64 s[100:101], s99, v4
	s_nop 1
	v_cndmask_b32_e64 v131, v165, v131, s[100:101]
	v_sub_f32_e32 v132, v162, v131
	v_fmamk_f32 v2, v66, 0x3e38aa3b, v132
	v_exp_f32_e32 v8, v2
	v_fmamk_f32 v5, v67, 0x3e38aa3b, v132
	v_exp_f32_e32 v12, v5
	v_fmamk_f32 v5, v68, 0x3e38aa3b, v132
	v_exp_f32_e32 v9, v5
	v_fmamk_f32 v5, v69, 0x3e38aa3b, v132
	v_exp_f32_e32 v13, v5
	v_fmamk_f32 v5, v70, 0x3e38aa3b, v132
	v_add_f32_e32 v4, 0, v8
	v_exp_f32_e32 v10, v5
	v_fmamk_f32 v5, v71, 0x3e38aa3b, v132
	v_exp_f32_e32 v14, v5
	v_fmamk_f32 v5, v72, 0x3e38aa3b, v132
	v_add_f32_e32 v4, v12, v4
	v_exp_f32_e32 v11, v5
	v_fmamk_f32 v5, v73, 0x3e38aa3b, v132
	v_add_f32_e32 v4, v9, v4
	v_exp_f32_e32 v15, v5
	v_fmamk_f32 v5, v74, 0x3e38aa3b, v132
	v_add_f32_e32 v4, v13, v4
	v_exp_f32_e32 v66, v5
	v_fmamk_f32 v5, v75, 0x3e38aa3b, v132
	v_add_f32_e32 v4, v10, v4
	v_exp_f32_e32 v67, v5
	v_fmamk_f32 v5, v76, 0x3e38aa3b, v132
	v_add_f32_e32 v4, v14, v4
	v_exp_f32_e32 v68, v5
	v_fmamk_f32 v5, v77, 0x3e38aa3b, v132
	v_add_f32_e32 v4, v11, v4
	v_exp_f32_e32 v69, v5
	v_fmamk_f32 v5, v78, 0x3e38aa3b, v132
	v_add_f32_e32 v4, v15, v4
	v_add_f32_e32 v4, v66, v4
	v_exp_f32_e32 v70, v5
	v_fmamk_f32 v5, v79, 0x3e38aa3b, v132
	v_add_f32_e32 v4, v67, v4
	v_exp_f32_e32 v71, v5
	v_fmamk_f32 v5, v80, 0x3e38aa3b, v132
	v_add_f32_e32 v4, v68, v4
	v_exp_f32_e32 v72, v5
	v_fmamk_f32 v5, v81, 0x3e38aa3b, v132
	v_add_f32_e32 v4, v69, v4
	v_exp_f32_e32 v73, v5
	v_fmamk_f32 v5, v50, 0x3e38aa3b, v132
	v_add_f32_e32 v4, v70, v4
	v_exp_f32_e32 v50, v5
	v_fmamk_f32 v5, v51, 0x3e38aa3b, v132
	v_add_f32_e32 v4, v71, v4
	v_exp_f32_e32 v51, v5
	v_fmamk_f32 v5, v52, 0x3e38aa3b, v132
	v_add_f32_e32 v4, v72, v4
	v_exp_f32_e32 v52, v5
	v_fmamk_f32 v5, v53, 0x3e38aa3b, v132
	v_add_f32_e32 v4, v73, v4
	v_exp_f32_e32 v53, v5
	v_fmamk_f32 v5, v54, 0x3e38aa3b, v132
	v_add_f32_e32 v4, v50, v4
	v_exp_f32_e32 v54, v5
	v_fmamk_f32 v5, v55, 0x3e38aa3b, v132
	v_add_f32_e32 v4, v51, v4
	v_exp_f32_e32 v55, v5
	v_fmamk_f32 v5, v56, 0x3e38aa3b, v132
	v_add_f32_e32 v4, v52, v4
	v_exp_f32_e32 v56, v5
	v_fmamk_f32 v5, v57, 0x3e38aa3b, v132
	v_add_f32_e32 v4, v53, v4
	v_exp_f32_e32 v57, v5
	v_fmamk_f32 v5, v58, 0x3e38aa3b, v132
	v_add_f32_e32 v4, v54, v4
	v_exp_f32_e32 v58, v5
	v_fmamk_f32 v5, v59, 0x3e38aa3b, v132
	v_add_f32_e32 v4, v55, v4
	v_exp_f32_e32 v59, v5
	v_fmamk_f32 v5, v60, 0x3e38aa3b, v132
	v_add_f32_e32 v4, v56, v4
	v_exp_f32_e32 v60, v5
	v_add_f32_e32 v4, v57, v4
	v_add_f32_e32 v4, v58, v4
	v_add_f32_e32 v4, v59, v4
	v_sub_f32_e32 v2, v165, v131
	v_add_f32_e32 v74, v60, v4
	v_fmamk_f32 v4, v61, 0x3e38aa3b, v132
	v_exp_f32_e32 v2, v2
	v_exp_f32_e32 v61, v4
	ds_read_b64_tr_b16 v[4:5], v194 offset:8192
	ds_read_b64_tr_b16 v[6:7], v194 offset:9216
	v_cvt_pk_bf16_f32 v11, v11, v15
	v_cvt_pk_bf16_f32 v10, v10, v14
	v_cvt_pk_bf16_f32 v9, v9, v13
	v_cvt_pk_bf16_f32 v8, v8, v12
	ds_read_b64_tr_b16 v[14:15], v194 offset:9280
	ds_read_b64_tr_b16 v[12:13], v194 offset:8256
	s_cmp_eq_u64 s[100:101], 0
	s_cbranch_scc1 .Llz_ownA
	v_pk_mul_f32 v[48:49], v[48:49], v[2:3] op_sel_hi:[1,0]
	v_pk_mul_f32 v[46:47], v[46:47], v[2:3] op_sel_hi:[1,0]
	v_pk_mul_f32 v[44:45], v[44:45], v[2:3] op_sel_hi:[1,0]
	v_pk_mul_f32 v[42:43], v[42:43], v[2:3] op_sel_hi:[1,0]
	v_pk_mul_f32 v[40:41], v[40:41], v[2:3] op_sel_hi:[1,0]
	v_pk_mul_f32 v[38:39], v[38:39], v[2:3] op_sel_hi:[1,0]
	v_pk_mul_f32 v[36:37], v[36:37], v[2:3] op_sel_hi:[1,0]
	v_pk_mul_f32 v[34:35], v[34:35], v[2:3] op_sel_hi:[1,0]
	v_pk_mul_f32 v[32:33], v[32:33], v[2:3] op_sel_hi:[1,0]
	v_pk_mul_f32 v[30:31], v[30:31], v[2:3] op_sel_hi:[1,0]
	v_pk_mul_f32 v[28:29], v[28:29], v[2:3] op_sel_hi:[1,0]
	v_pk_mul_f32 v[26:27], v[26:27], v[2:3] op_sel_hi:[1,0]
	v_pk_mul_f32 v[24:25], v[24:25], v[2:3] op_sel_hi:[1,0]
	v_pk_mul_f32 v[22:23], v[22:23], v[2:3] op_sel_hi:[1,0]
	v_pk_mul_f32 v[20:21], v[20:21], v[2:3] op_sel_hi:[1,0]
	v_pk_mul_f32 v[18:19], v[18:19], v[2:3] op_sel_hi:[1,0]
	s_nop 1

; DI float fexp2(float x) { return __builtin_amdgcn_exp2f(x); }
; DI f32x16 mfma32(bf16x8 a, bf16x8 b, f32x16 c) { return __builtin_amdgcn_mfma_f32_32x32x16_bf16(a, b, c, 0, 0, 0); }
; template <int MASK, bool NEAR, int PASS>
; DI void flash_tile(Flash& st, const bf16x8 (&qf)[4], const char* kbuf, const char* vbuf, int pos0, int qpos, bool on,
;                    const float* lut, float bfar, float* imp_row, float rinv) {
;     ...
; #pragma unroll
;     for (int ks = 0; ks < 4; ++ks) {
;         const int ka = r * 128 + (((2 * ks + h) ^ ((r >> 1) & 7)) << 4);
;         const bf16x8 a0 = *(const bf16x8*)(kbuf + ka);
;         const bf16x8 a1 = *(const bf16x8*)(kbuf + 4096 + ka);
;         s[0] = mfma32(a0, qf[ks], s[0]);
;         s[1] = mfma32(a1, qf[ks], s[1]);
;     }
;     constexpr float c1 = 0.125f * LOG2E;
;     float alpha = 1.f;
;     float rs = 0.f;
;     if (!NEAR) {
;         const float bc = MASK == 2 ? 0.f : bfar;
;         float mref;
;         if (PASS != 2) {
;             float mr = s[0][0];
; #pragma unroll
;             for (int i = 1; i < 16; ++i) mr = fmaxf(mr, s[0][i]);
; #pragma unroll
;             for (int i = 0; i < 16; ++i) mr = fmaxf(mr, s[1][i]);
;             float mx = on ? mr * c1 + bc : -1e30f;
;             mx = fmaxf(mx, __shfl_xor(mx, 32));
;             const float mnew = fmaxf(st.m, mx);
;             alpha = fexp2(st.m - mnew);
;             st.m = mnew;
;             mref = mnew;
;         } else mref = st.m;
;         float bm = on ? bc - mref : -1e30f;
;         if (PASS == 2) bm = on ? bm + __log2f(rinv) : -1e30f;
; #pragma unroll
;         for (int tt = 0; tt < 2; ++tt)
; #pragma unroll
;             for (int i = 0; i < 16; ++i) { const float pv = fexp2(s[tt][i] * c1 + bm); s[tt][i] = pv; rs += pv; }
.LBB0_1531:
	s_cmp_eq_u64 exec, 0
	s_cbranch_scc1 .LBB0_1537
	v_add_u32_e32 v2, 0, v190
	ds_read_b128 v[50:53], v2 offset:16384
	ds_read_b128 v[130:133], v2 offset:20480
	v_add_u32_e32 v2, 0, v191
	ds_read_b128 v[142:145], v2 offset:16384
	ds_read_b128 v[12:15], v2 offset:20480
	v_add_u32_e32 v2, 0, v192
	ds_read_b128 v[138:141], v2 offset:16384
	ds_read_b128 v[8:11], v2 offset:20480
	v_add_u32_e32 v2, 0, v193
	ds_read_b128 v[134:137], v2 offset:16384
	ds_read_b128 v[4:7], v2 offset:20480
	s_waitcnt lgkmcnt(8)
	v_add_u32_e32 v2, 0xb0, v16
	v_cmp_le_i32_e32 vcc, v2, v158
	s_and_saveexec_b64 s[2:3], vcc
	s_xor_b64 s[2:3], exec, s[2:3]
	s_cbranch_execz .LBB0_1534
	s_waitcnt lgkmcnt(7)
	v_mfma_f32_32x32x16_bf16 v[66:81], v[50:53], v[82:85], 0
	s_waitcnt lgkmcnt(5)
	v_mfma_f32_32x32x16_bf16 v[66:81], v[142:145], v[86:89], v[66:81]
	v_mfma_f32_32x32x16_bf16 v[50:65], v[130:133], v[82:85], 0
	s_waitcnt lgkmcnt(3)
	v_mfma_f32_32x32x16_bf16 v[66:81], v[138:141], v[90:93], v[66:81]
	v_mfma_f32_32x32x16_bf16 v[50:65], v[12:15], v[86:89], v[50:65]
	s_waitcnt lgkmcnt(1)
	v_mfma_f32_32x32x16_bf16 v[66:81], v[134:137], v[94:97], v[66:81]
	v_mfma_f32_32x32x16_bf16 v[50:65], v[8:11], v[90:93], v[50:65]
	s_nop 10
	v_max_f32_e32 v2, v67, v67
	v_max_f32_e32 v12, v66, v66
	v_max_f32_e32 v2, v12, v2
	v_max3_f32 v2, v2, v68, v69
	v_max3_f32 v2, v2, v70, v71
	v_max3_f32 v2, v2, v72, v73
	v_max3_f32 v2, v2, v74, v75
	s_waitcnt lgkmcnt(0)
	v_mfma_f32_32x32x16_bf16 v[50:65], v[4:7], v[94:97], v[50:65]
	v_max3_f32 v2, v2, v76, v77
	v_max3_f32 v2, v2, v78, v79
	v_max3_f32 v2, v2, v80, v81
	v_and_b32_e32 v5, 64, v188
	v_xor_b32_e32 v4, 32, v188
	v_add_u32_e32 v5, 64, v5
	v_cmp_lt_i32_e32 vcc, v4, v5
	s_nop 4
	v_max3_f32 v2, v2, v50, v51
	v_max3_f32 v2, v2, v52, v53
	v_max3_f32 v2, v2, v54, v55
	v_max3_f32 v2, v2, v56, v57
	v_max3_f32 v2, v2, v58, v59
	v_max3_f32 v2, v2, v60, v61
	v_max3_f32 v2, v2, v62, v63
	v_max3_f32 v2, v2, v64, v65
	v_cndmask_b32_e32 v4, v188, v4, vcc
	v_fmamk_f32 v2, v2, 0x3e38aa3b, v162
	v_lshlrev_b32_e32 v16, 2, v4
	v_mov_b32_e32 v4, v2
	s_nop 1
	v_permlane32_swap_b32_e32 v2, v4
	v_max3_f32 v17, v165, v2, v4
	s_mov_b32 s99, 0x41000000
	v_sub_f32_e32 v4, v17, v165
	v_cmp_lt_f32_e64 s[100:101], s99, v4
	s_nop 1
	v_cndmask_b32_e64 v17, v165, v17, s[100:101]
	v_sub_f32_e32 v130, v162, v17
	v_fmamk_f32 v2, v66, 0x3e38aa3b, v130
	v_exp_f32_e32 v8, v2
	v_fmamk_f32 v5, v67, 0x3e38aa3b, v130
	v_exp_f32_e32 v12, v5
	v_fmamk_f32 v5, v68, 0x3e38aa3b, v130
	v_exp_f32_e32 v9, v5
	v_fmamk_f32 v5, v69, 0x3e38aa3b, v130
	v_exp_f32_e32 v13, v5
	v_fmamk_f32 v5, v70, 0x3e38aa3b, v130
	v_add_f32_e32 v4, 0, v8
	v_exp_f32_e32 v10, v5
	v_fmamk_f32 v5, v71, 0x3e38aa3b, v130
	v_exp_f32_e32 v14, v5
	v_fmamk_f32 v5, v72, 0x3e38aa3b, v130
	v_add_f32_e32 v4, v12, v4
	v_exp_f32_e32 v11, v5
	v_fmamk_f32 v5, v73, 0x3e38aa3b, v130
	v_add_f32_e32 v4, v9, v4
	v_exp_f32_e32 v15, v5
	v_fmamk_f32 v5, v74, 0x3e38aa3b, v130
	v_add_f32_e32 v4, v13, v4
	v_exp_f32_e32 v66, v5
	v_fmamk_f32 v5, v75, 0x3e38aa3b, v130
	v_add_f32_e32 v4, v10, v4
	v_exp_f32_e32 v67, v5
	v_fmamk_f32 v5, v76, 0x3e38aa3b, v130
	v_add_f32_e32 v4, v14, v4
	v_exp_f32_e32 v68, v5
	v_fmamk_f32 v5, v77, 0x3e38aa3b, v130
	v_add_f32_e32 v4, v11, v4
	v_exp_f32_e32 v69, v5
	v_fmamk_f32 v5, v78, 0x3e38aa3b, v130
	v_add_f32_e32 v4, v15, v4
	v_add_f32_e32 v4, v66, v4
	v_exp_f32_e32 v70, v5
	v_fmamk_f32 v5, v79, 0x3e38aa3b, v130
	v_add_f32_e32 v4, v67, v4
	v_exp_f32_e32 v71, v5
	v_fmamk_f32 v5, v80, 0x3e38aa3b, v130
	v_add_f32_e32 v4, v68, v4
	v_exp_f32_e32 v72, v5
	v_fmamk_f32 v5, v81, 0x3e38aa3b, v130
	v_add_f32_e32 v4, v69, v4
	v_exp_f32_e32 v73, v5
	v_fmamk_f32 v5, v50, 0x3e38aa3b, v130
	v_add_f32_e32 v4, v70, v4
	v_exp_f32_e32 v50, v5
	v_fmamk_f32 v5, v51, 0x3e38aa3b, v130
	v_add_f32_e32 v4, v71, v4
	v_exp_f32_e32 v51, v5
	v_fmamk_f32 v5, v52, 0x3e38aa3b, v130
	v_add_f32_e32 v4, v72, v4
	v_exp_f32_e32 v52, v5
	v_fmamk_f32 v5, v53, 0x3e38aa3b, v130
	v_add_f32_e32 v4, v73, v4
	v_exp_f32_e32 v53, v5
	v_fmamk_f32 v5, v54, 0x3e38aa3b, v130
	v_add_f32_e32 v4, v50, v4
	v_exp_f32_e32 v54, v5
	v_fmamk_f32 v5, v55, 0x3e38aa3b, v130
	v_add_f32_e32 v4, v51, v4
	v_exp_f32_e32 v55, v5
	v_fmamk_f32 v5, v56, 0x3e38aa3b, v130
	v_add_f32_e32 v4, v52, v4
	v_exp_f32_e32 v56, v5
	v_fmamk_f32 v5, v57, 0x3e38aa3b, v130
	v_add_f32_e32 v4, v53, v4
	v_exp_f32_e32 v57, v5
	v_fmamk_f32 v5, v58, 0x3e38aa3b, v130
	v_add_f32_e32 v4, v54, v4
	v_exp_f32_e32 v58, v5
	v_fmamk_f32 v5, v59, 0x3e38aa3b, v130
	v_add_f32_e32 v4, v55, v4
	v_exp_f32_e32 v59, v5
	v_fmamk_f32 v5, v60, 0x3e38aa3b, v130
	v_add_f32_e32 v4, v56, v4
	v_exp_f32_e32 v60, v5
	v_add_f32_e32 v4, v57, v4
	v_add_f32_e32 v4, v58, v4
	v_add_f32_e32 v4, v59, v4
	v_sub_f32_e32 v2, v165, v17
	v_add_f32_e32 v74, v60, v4
	v_fmamk_f32 v4, v61, 0x3e38aa3b, v130
	v_exp_f32_e32 v2, v2
	v_exp_f32_e32 v61, v4
	ds_read_b64_tr_b16 v[4:5], v194 offset:24576
	ds_read_b64_tr_b16 v[6:7], v194 offset:25600
	v_cvt_pk_bf16_f32 v11, v11, v15
	v_cvt_pk_bf16_f32 v10, v10, v14
	v_cvt_pk_bf16_f32 v9, v9, v13
	v_cvt_pk_bf16_f32 v8, v8, v12
	ds_read_b64_tr_b16 v[14:15], v194 offset:25664
	ds_read_b64_tr_b16 v[12:13], v194 offset:24640
	s_cmp_eq_u64 s[100:101], 0
	s_cbranch_scc1 .Llz_ownB
	v_pk_mul_f32 v[48:49], v[48:49], v[2:3] op_sel_hi:[1,0]
	v_pk_mul_f32 v[46:47], v[46:47], v[2:3] op_sel_hi:[1,0]
	v_pk_mul_f32 v[44:45], v[44:45], v[2:3] op_sel_hi:[1,0]
	v_pk_mul_f32 v[42:43], v[42:43], v[2:3] op_sel_hi:[1,0]
	v_pk_mul_f32 v[40:41], v[40:41], v[2:3] op_sel_hi:[1,0]
	v_pk_mul_f32 v[38:39], v[38:39], v[2:3] op_sel_hi:[1,0]
	v_pk_mul_f32 v[36:37], v[36:37], v[2:3] op_sel_hi:[1,0]
	v_pk_mul_f32 v[34:35], v[34:35], v[2:3] op_sel_hi:[1,0]
	v_pk_mul_f32 v[32:33], v[32:33], v[2:3] op_sel_hi:[1,0]
	v_pk_mul_f32 v[30:31], v[30:31], v[2:3] op_sel_hi:[1,0]
	v_pk_mul_f32 v[28:29], v[28:29], v[2:3] op_sel_hi:[1,0]
	v_pk_mul_f32 v[26:27], v[26:27], v[2:3] op_sel_hi:[1,0]
	v_pk_mul_f32 v[24:25], v[24:25], v[2:3] op_sel_hi:[1,0]
	v_pk_mul_f32 v[22:23], v[22:23], v[2:3] op_sel_hi:[1,0]
	v_pk_mul_f32 v[20:21], v[20:21], v[2:3] op_sel_hi:[1,0]
	v_pk_mul_f32 v[18:19], v[18:19], v[2:3] op_sel_hi:[1,0]
	s_nop 1
